# attention softmax masking made branch-free: batched bias LDS lookups + v_cndmask instead of 80 exec-masked blocks
# baseline (speedup 1.0000x reference)
; #define LAS __attribute__((address_space(3)))
; __device__ __forceinline__ float lo16(unsigned v) { return __uint_as_float(v << 16); }
; __device__ __forceinline__ float hi16(unsigned v) { return __uint_as_float(v & 0xffff0000u); }
; __device__ __forceinline__ void attn_item(const Params& P, int slice, int item, LAS unsigned char* lds) {
;     ...
;   const int dil = 1 << (2 * gi), M = L / dil, cps = L >> 7, b = ci / cps, cr = ci % cps, cpr = M >> 7, r = cr / cpr, chunk = cr % cpr, m0 = chunk * 128, head = gi * 4 + g;
;   const u16* qkv = (const u16*)(ws + O_QKV);
;   LAS unsigned char* img = lds + half * KHALF;
;   LAS float* bl = (LAS float*)(lds + 2 * KHALF + half * 1024);
;   stage_kv(qkv + 1536 + head * 128, b, L, dil, r, m0, M, img, P.in[I_GK], ht);
;   if (ht < 129) bl[ht] = ((const float*)(ws + O_BIAS))[head * 129 + ht];
;   const int mq = m0 + 32 * wq + qn, tokq = b * L + mq * dil + r;
;   bf16x8 Qf[8];
;   {
;     u32x4 qv[8]; float s = 0.f;
; #pragma unroll
;     for (int ks = 0; ks < 8; ++ks) { qv[ks] = *(const u32x4*)(qkv + (size_t)tokq * 4608 + head * 128 + 16 * ks + 8 * h);
;       const float f0 = lo16(qv[ks].x), f1 = hi16(qv[ks].x), f2 = lo16(qv[ks].y), f3 = hi16(qv[ks].y), f4 = lo16(qv[ks].z), f5 = hi16(qv[ks].z), f6 = lo16(qv[ks].w), f7 = hi16(qv[ks].w);
;       s += f0 * f0 + f1 * f1 + f2 * f2 + f3 * f3 + f4 * f4 + f5 * f5 + f6 * f6 + f7 * f7; }
;     s += __shfl_xor(s, 32);
;     const float rs = rsqrtf(s * (1.0f / 128.0f) + 1e-6f) * 0.08838834764831845f;
.LBB0_658:
	s_or_b64 exec, exec, s[92:93]
	s_lshr_b32 s72, s72, 1
	v_and_b32_e32 v102, 31, v107
	s_and_b32 s72, s72, 0x60
	v_or_b32_e32 v68, s72, v102
	v_or_b32_e32 v169, s74, v68
	v_lshlrev_b32_e32 v0, s73, v169
	v_add_u32_e32 v106, s75, v0
	v_mov_b64_e32 v[0:1], s[4:5]
	v_bfe_u32 v103, v107, 5, 1
	v_mad_i64_i32 v[0:1], s[74:75], v106, s31, v[0:1]
	v_lshl_add_u64 v[0:1], s[0:1], 1, v[0:1]
	v_lshlrev_b32_e32 v36, 4, v103
	v_mov_b32_e32 v37, v81
	v_lshl_add_u64 v[38:39], v[0:1], 0, v[36:37]
	s_mov_b64 s[0:1], 0x16852000
	v_lshl_add_u64 v[40:41], v[38:39], 0, s[0:1]
	flat_load_dwordx4 v[46:49], v[40:41] offset:192
	flat_load_dwordx4 v[56:59], v[40:41] offset:160
	flat_load_dwordx4 v[70:73], v[40:41] offset:128
	flat_load_dwordx4 v[74:77], v[40:41] offset:224
	v_and_b32_e32 v0, 64, v225
	v_xor_b32_e32 v37, 32, v225
	v_add_u32_e32 v42, 64, v0
	v_and_b32_e32 v69, 32, v107
	v_cmp_lt_i32_e32 vcc, v37, v42
	s_mov_b32 s0, 0x16852000
	global_load_dwordx4 v[28:31], v69, s[46:47] offset:16
	global_load_dwordx4 v[32:35], v69, s[46:47]
	global_load_dwordx4 v[20:23], v69, s[46:47] offset:80
	global_load_dwordx4 v[24:27], v69, s[46:47] offset:64
	global_load_dwordx4 v[12:15], v69, s[46:47] offset:144
	global_load_dwordx4 v[16:19], v69, s[46:47] offset:128
	global_load_dwordx4 v[4:7], v69, s[46:47] offset:208
	global_load_dwordx4 v[8:11], v69, s[46:47] offset:192
	global_load_dwordx4 v[0:3], v69, s[46:47] offset:256
	v_cndmask_b32_e32 v37, v225, v37, vcc
	v_add_co_u32_e32 v38, vcc, s0, v38
	flat_load_dwordx4 v[82:85], v[40:41] offset:96
	s_nop 0
	v_addc_co_u32_e32 v39, vcc, 0, v39, vcc
	flat_load_dwordx4 v[86:89], v[40:41] offset:32
	flat_load_dwordx4 v[90:93], v[40:41] offset:64
	flat_load_dwordx4 v[94:97], v[38:39]
	v_lshlrev_b32_e32 v170, 2, v37
	s_mov_b32 s0, 0x800000
	v_lshlrev_b32_e32 v168, 2, v103
	s_add_i32 s71, s71, s72
	s_cmp_gt_i32 s71, -1
	s_waitcnt vmcnt(0) lgkmcnt(0)
	v_and_b32_e32 v45, 0xffff0000, v46
	v_lshlrev_b32_e32 v50, 16, v59
	v_and_b32_e32 v51, 0xffff0000, v59
	v_lshlrev_b32_e32 v54, 16, v58
	v_and_b32_e32 v55, 0xffff0000, v58
	v_lshlrev_b32_e32 v58, 16, v57
	v_and_b32_e32 v59, 0xffff0000, v57
	v_and_b32_e32 v57, 0xffff0000, v74
	v_lshlrev_b32_e32 v44, 16, v46
	v_lshlrev_b32_e32 v60, 16, v56
	v_and_b32_e32 v61, 0xffff0000, v56
	v_lshlrev_b32_e32 v56, 16, v74
	v_mov_b32_e32 v110, v45
	v_mov_b32_e32 v111, v57
	v_lshlrev_b32_e32 v42, 16, v47
	v_and_b32_e32 v67, 0xffff0000, v70
	v_lshlrev_b32_e32 v52, 16, v75
	v_mov_b32_e32 v108, v44
	v_mov_b32_e32 v109, v56
	v_pk_mul_f32 v[110:111], v[110:111], v[110:111]
	v_and_b32_e32 v43, 0xffff0000, v47
	v_lshlrev_b32_e32 v66, 16, v70
	v_and_b32_e32 v53, 0xffff0000, v75
	v_mov_b32_e32 v78, v42
	v_mov_b32_e32 v79, v52
	v_pk_fma_f32 v[108:109], v[108:109], v[108:109], v[110:111]
	v_mov_b32_e32 v112, v67
	v_mov_b32_e32 v113, v61
	v_lshlrev_b32_e32 v40, 16, v48
	v_and_b32_e32 v41, 0xffff0000, v48
	v_lshlrev_b32_e32 v64, 16, v71
	v_lshlrev_b32_e32 v48, 16, v76
	v_mov_b32_e32 v104, v43
	v_mov_b32_e32 v105, v53
	v_pk_fma_f32 v[78:79], v[78:79], v[78:79], v[108:109]
	v_mov_b32_e32 v110, v66
	v_mov_b32_e32 v111, v60
	v_pk_mul_f32 v[112:113], v[112:113], v[112:113]
	v_lshlrev_b32_e32 v38, 16, v49
	v_and_b32_e32 v39, 0xffff0000, v49
	v_and_b32_e32 v65, 0xffff0000, v71
	v_and_b32_e32 v49, 0xffff0000, v76
	v_mov_b32_e32 v74, v40
	v_mov_b32_e32 v75, v48
	v_pk_fma_f32 v[78:79], v[104:105], v[104:105], v[78:79]
	v_mov_b32_e32 v104, v64
	v_mov_b32_e32 v105, v58
	v_pk_fma_f32 v[110:111], v[110:111], v[110:111], v[112:113]
	v_lshlrev_b32_e32 v100, 16, v72
	v_lshlrev_b32_e32 v46, 16, v77
	v_and_b32_e32 v47, 0xffff0000, v77
	v_mov_b32_e32 v76, v41
	v_mov_b32_e32 v77, v49
	v_pk_fma_f32 v[74:75], v[74:75], v[74:75], v[78:79]
	v_mov_b32_e32 v108, v65
	v_mov_b32_e32 v109, v59
	v_pk_fma_f32 v[104:105], v[104:105], v[104:105], v[110:111]
	v_pk_fma_f32 v[74:75], v[76:77], v[76:77], v[74:75]
	v_mov_b32_e32 v76, v100
	v_mov_b32_e32 v77, v54
	v_pk_fma_f32 v[104:105], v[108:109], v[108:109], v[104:105]
	v_and_b32_e32 v101, 0xffff0000, v72
	v_pk_fma_f32 v[76:77], v[76:77], v[76:77], v[104:105]
	v_and_b32_e32 v105, 0xffff0000, v82
	v_and_b32_e32 v141, 0xffff0000, v90
	v_mov_b32_e32 v70, v38
	v_mov_b32_e32 v71, v46
	v_mov_b32_e32 v78, v101
	v_mov_b32_e32 v79, v55
	v_lshlrev_b32_e32 v104, 16, v82
	v_lshlrev_b32_e32 v140, 16, v90
	v_mov_b32_e32 v116, v141
	v_mov_b32_e32 v117, v105
	v_lshlrev_b32_e32 v62, 16, v73
	v_and_b32_e32 v63, 0xffff0000, v73
	v_mov_b32_e32 v72, v39
	v_mov_b32_e32 v73, v47
	v_pk_fma_f32 v[70:71], v[70:71], v[70:71], v[74:75]
	v_pk_fma_f32 v[76:77], v[78:79], v[78:79], v[76:77]
	v_lshlrev_b32_e32 v78, 16, v83
	v_lshlrev_b32_e32 v138, 16, v92
	v_and_b32_e32 v139, 0xffff0000, v92
	v_lshlrev_b32_e32 v92, 16, v91
	v_mov_b32_e32 v114, v140
	v_mov_b32_e32 v115, v104
	v_pk_mul_f32 v[116:117], v[116:117], v[116:117]
	v_pk_fma_f32 v[70:71], v[72:73], v[72:73], v[70:71]
	v_mov_b32_e32 v72, v62
	v_mov_b32_e32 v73, v50
	v_and_b32_e32 v79, 0xffff0000, v83
	v_lshlrev_b32_e32 v136, 16, v93
	v_and_b32_e32 v137, 0xffff0000, v93
	v_and_b32_e32 v93, 0xffff0000, v91
	v_mov_b32_e32 v110, v92
	v_mov_b32_e32 v111, v78
	v_pk_fma_f32 v[114:115], v[114:115], v[114:115], v[116:117]
	v_pk_fma_f32 v[72:73], v[72:73], v[72:73], v[76:77]
	v_lshlrev_b32_e32 v76, 16, v84
	v_mov_b32_e32 v112, v93
	v_mov_b32_e32 v113, v79
	v_pk_fma_f32 v[110:111], v[110:111], v[110:111], v[114:115]
	v_mov_b32_e32 v74, v63
	v_mov_b32_e32 v75, v51
	v_and_b32_e32 v77, 0xffff0000, v84
	v_mov_b32_e32 v90, v138
	v_mov_b32_e32 v91, v76
	v_pk_fma_f32 v[110:111], v[112:113], v[112:113], v[110:111]
	v_pk_fma_f32 v[72:73], v[74:75], v[74:75], v[72:73]
	v_lshlrev_b32_e32 v74, 16, v85
; #define LAS __attribute__((address_space(3)))
; __device__ __forceinline__ unsigned pk2(float lo, float hi) { const f32x2_t f = {lo, hi}; const bf16x2_t b = __builtin_convertvector(f, bf16x2_t); return __builtin_bit_cast(unsigned, b); }
; __device__ __forceinline__ float lo16(unsigned v) { return __uint_as_float(v << 16); }
; __device__ __forceinline__ float hi16(unsigned v) { return __uint_as_float(v & 0xffff0000u); }
; __device__ __forceinline__ void attn_item(const Params& P, int slice, int item, LAS unsigned char* lds) {
;     ...
;     for (int ks = 0; ks < 8; ++ks) { qv[ks] = *(const u32x4*)(qkv + (size_t)tokq * 4608 + head * 128 + 16 * ks + 8 * h);
;       const float f0 = lo16(qv[ks].x), f1 = hi16(qv[ks].x), f2 = lo16(qv[ks].y), f3 = hi16(qv[ks].y), f4 = lo16(qv[ks].z), f5 = hi16(qv[ks].z), f6 = lo16(qv[ks].w), f7 = hi16(qv[ks].w);
;       s += f0 * f0 + f1 * f1 + f2 * f2 + f3 * f3 + f4 * f4 + f5 * f5 + f6 * f6 + f7 * f7; }
;     s += __shfl_xor(s, 32);
;     const float rs = rsqrtf(s * (1.0f / 128.0f) + 1e-6f) * 0.08838834764831845f;
;     const float* gq = P.in[I_GQ];
; #pragma unroll
;     for (int ks = 0; ks < 8; ++ks) {
;       const f32x4 g0 = *(const f32x4*)(gq + 16 * ks + 8 * h), g1 = *(const f32x4*)(gq + 16 * ks + 8 * h + 4);
;       u32x4 o; o.x = pk2(lo16(qv[ks].x) * rs * g0[0], hi16(qv[ks].x) * rs * g0[1]); o.y = pk2(lo16(qv[ks].y) * rs * g0[2], hi16(qv[ks].y) * rs * g0[3]);
;       o.z = pk2(lo16(qv[ks].z) * rs * g1[0], hi16(qv[ks].z) * rs * g1[1]); o.w = pk2(lo16(qv[ks].w) * rs * g1[2], hi16(qv[ks].w) * rs * g1[3]);
;       Qf[ks] = __builtin_bit_cast(bf16x8, o);
;     }
;   }
;   __syncthreads();
;   f32x16 sc[5];
; #pragma unroll
;   for (int kt = 0; kt < 5; ++kt) {
; #pragma unroll
;     for (int i = 0; i < 16; ++i) sc[kt][i] = 0.f;
;     const LAS unsigned char* kp = img + (32 * wq + 32 * kt + qn) * KROW + 16 * h;
; #pragma unroll
;     for (int ks = 0; ks < 8; ++ks) { const bf16x8 a = *(const LAS bf16x8*)(kp + 32 * ks); sc[kt] = __builtin_amdgcn_mfma_f32_32x32x16_bf16(a, Qf[ks], sc[kt], 0, 0, 0); }
	v_mov_b32_e32 v108, v139
	v_mov_b32_e32 v109, v77
	v_pk_fma_f32 v[90:91], v[90:91], v[90:91], v[110:111]
	v_and_b32_e32 v75, 0xffff0000, v85
	v_mov_b32_e32 v82, v136
	v_mov_b32_e32 v83, v74
	v_pk_fma_f32 v[90:91], v[108:109], v[108:109], v[90:91]
	v_and_b32_e32 v145, 0xffff0000, v86
	v_and_b32_e32 v147, 0xffff0000, v94
	v_mov_b32_e32 v84, v137
	v_mov_b32_e32 v85, v75
	v_pk_fma_f32 v[82:83], v[82:83], v[82:83], v[90:91]
	v_lshlrev_b32_e32 v144, 16, v86
	v_lshlrev_b32_e32 v146, 16, v94
	v_mov_b32_e32 v120, v147
	v_mov_b32_e32 v121, v145
	v_pk_fma_f32 v[82:83], v[84:85], v[84:85], v[82:83]
	v_lshlrev_b32_e32 v142, 16, v88
	v_and_b32_e32 v143, 0xffff0000, v88
	v_lshlrev_b32_e32 v88, 16, v87
	v_lshlrev_b32_e32 v84, 16, v96
	v_and_b32_e32 v85, 0xffff0000, v96
	v_lshlrev_b32_e32 v96, 16, v95
	v_mov_b32_e32 v118, v146
	v_mov_b32_e32 v119, v144
	v_pk_mul_f32 v[120:121], v[120:121], v[120:121]
	v_lshlrev_b32_e32 v90, 16, v89
	v_and_b32_e32 v91, 0xffff0000, v89
	v_and_b32_e32 v89, 0xffff0000, v87
	v_lshlrev_b32_e32 v86, 16, v97
	v_and_b32_e32 v87, 0xffff0000, v97
	v_and_b32_e32 v97, 0xffff0000, v95
	v_mov_b32_e32 v114, v96
	v_mov_b32_e32 v115, v88
	v_pk_fma_f32 v[118:119], v[118:119], v[118:119], v[120:121]
	v_mov_b32_e32 v116, v97
	v_mov_b32_e32 v117, v89
	v_pk_fma_f32 v[114:115], v[114:115], v[114:115], v[118:119]
	v_mov_b32_e32 v110, v84
	v_mov_b32_e32 v111, v142
	v_pk_fma_f32 v[114:115], v[116:117], v[116:117], v[114:115]
	v_mov_b32_e32 v112, v85
	v_mov_b32_e32 v113, v143
	v_pk_fma_f32 v[110:111], v[110:111], v[110:111], v[114:115]
	v_mov_b32_e32 v94, v86
	v_mov_b32_e32 v95, v90
	v_pk_fma_f32 v[110:111], v[112:113], v[112:113], v[110:111]
	v_mov_b32_e32 v108, v87
	v_mov_b32_e32 v109, v91
	v_pk_fma_f32 v[94:95], v[94:95], v[94:95], v[110:111]
	s_nop 0
	v_pk_fma_f32 v[94:95], v[108:109], v[108:109], v[94:95]
	global_load_dwordx4 v[108:111], v69, s[46:47] offset:272
	global_load_dwordx4 v[112:115], v69, s[46:47] offset:336
	global_load_dwordx4 v[116:119], v69, s[46:47] offset:320
	v_add_f32_e32 v37, v94, v95
	v_add_f32_e32 v37, v37, v82
	v_add_f32_e32 v37, v37, v83
	v_add_f32_e32 v37, v37, v72
	v_add_f32_e32 v37, v37, v73
	v_add_f32_e32 v37, v37, v70
	v_add_f32_e32 v37, v37, v71
	ds_bpermute_b32 v70, v170, v37
	global_load_dwordx4 v[120:123], v69, s[46:47] offset:400
	global_load_dwordx4 v[124:127], v69, s[46:47] offset:384
	global_load_dwordx4 v[128:131], v69, s[46:47] offset:464
	global_load_dwordx4 v[132:135], v69, s[46:47] offset:448
	s_waitcnt lgkmcnt(0)
	s_barrier
	v_add_f32_e32 v37, v37, v70
	v_fmamk_f32 v37, v37, 0x3c000000, v218
	v_mul_f32_e32 v70, 0x4b800000, v37
	v_cmp_gt_f32_e32 vcc, s0, v37
	s_movk_i32 s0, 0x81
	s_nop 0
	v_cndmask_b32_e32 v37, v37, v70, vcc
	v_rsq_f32_e32 v37, v37
	s_nop 0
	v_mul_f32_e32 v69, 0x45800000, v37
	v_cndmask_b32_e32 v37, v37, v69, vcc
	v_mul_f32_e32 v148, 0x3db504f3, v37
	v_pk_mul_f32 v[70:71], v[148:149], v[146:147] op_sel_hi:[0,1]
	v_pk_mul_f32 v[32:33], v[32:33], v[70:71]
	s_nop 0
	v_cvt_pk_bf16_f32 v82, v32, v33
	v_pk_mul_f32 v[32:33], v[148:149], v[96:97] op_sel_hi:[0,1]
	v_pk_mul_f32 v[32:33], v[34:35], v[32:33]
	s_nop 0
	v_cvt_pk_bf16_f32 v83, v32, v33
	v_pk_mul_f32 v[32:33], v[148:149], v[84:85] op_sel_hi:[0,1]
	v_pk_mul_f32 v[28:29], v[28:29], v[32:33]
	s_nop 0
	v_cvt_pk_bf16_f32 v84, v28, v29
	v_pk_mul_f32 v[28:29], v[148:149], v[86:87] op_sel_hi:[0,1]
	v_pk_mul_f32 v[28:29], v[30:31], v[28:29]
	s_nop 0
	v_cvt_pk_bf16_f32 v85, v28, v29
	v_pk_mul_f32 v[28:29], v[148:149], v[144:145] op_sel_hi:[0,1]
	v_pk_mul_f32 v[24:25], v[24:25], v[28:29]
	s_nop 0
	v_cvt_pk_bf16_f32 v86, v24, v25
	v_pk_mul_f32 v[24:25], v[148:149], v[88:89] op_sel_hi:[0,1]
	v_pk_mul_f32 v[24:25], v[26:27], v[24:25]
	s_nop 0
	v_cvt_pk_bf16_f32 v87, v24, v25
	v_pk_mul_f32 v[24:25], v[148:149], v[142:143] op_sel_hi:[0,1]
	v_pk_mul_f32 v[20:21], v[20:21], v[24:25]
	s_nop 0
	v_cvt_pk_bf16_f32 v88, v20, v21
	v_pk_mul_f32 v[20:21], v[148:149], v[90:91] op_sel_hi:[0,1]
	v_pk_mul_f32 v[20:21], v[22:23], v[20:21]
	s_nop 0
	v_cvt_pk_bf16_f32 v89, v20, v21
	v_pk_mul_f32 v[20:21], v[148:149], v[140:141] op_sel_hi:[0,1]
	v_pk_mul_f32 v[16:17], v[16:17], v[20:21]
	s_nop 0
	v_cvt_pk_bf16_f32 v90, v16, v17
	v_pk_mul_f32 v[16:17], v[148:149], v[92:93] op_sel_hi:[0,1]
	v_pk_mul_f32 v[16:17], v[18:19], v[16:17]
	s_nop 0
	v_cvt_pk_bf16_f32 v91, v16, v17
	v_pk_mul_f32 v[16:17], v[148:149], v[138:139] op_sel_hi:[0,1]
	v_pk_mul_f32 v[12:13], v[12:13], v[16:17]
	s_nop 0
	v_cvt_pk_bf16_f32 v92, v12, v13
	v_pk_mul_f32 v[12:13], v[148:149], v[136:137] op_sel_hi:[0,1]
	v_pk_mul_f32 v[12:13], v[14:15], v[12:13]
	s_nop 0
	v_cvt_pk_bf16_f32 v93, v12, v13
	v_pk_mul_f32 v[12:13], v[148:149], v[104:105] op_sel_hi:[0,1]
	v_pk_mul_f32 v[8:9], v[8:9], v[12:13]
	s_nop 0
	v_cvt_pk_bf16_f32 v94, v8, v9
	v_pk_mul_f32 v[8:9], v[148:149], v[78:79] op_sel_hi:[0,1]
	v_pk_mul_f32 v[8:9], v[10:11], v[8:9]
	s_nop 0
	v_cvt_pk_bf16_f32 v95, v8, v9
	v_pk_mul_f32 v[8:9], v[148:149], v[76:77] op_sel_hi:[0,1]
	v_pk_mul_f32 v[4:5], v[4:5], v[8:9]
	v_mul_u32_u24_e32 v8, 0x110, v68
	v_add3_u32 v104, s64, v36, v8
	ds_read_b128 v[8:11], v104
	v_cvt_pk_bf16_f32 v96, v4, v5
	v_pk_mul_f32 v[4:5], v[148:149], v[74:75] op_sel_hi:[0,1]
	v_pk_mul_f32 v[4:5], v[6:7], v[4:5]
	s_nop 0
	v_cvt_pk_bf16_f32 v97, v4, v5
	v_pk_mul_f32 v[4:5], v[148:149], v[66:67] op_sel_hi:[0,1]
	v_pk_mul_f32 v[0:1], v[0:1], v[4:5]
	s_nop 0
	v_cvt_pk_bf16_f32 v136, v0, v1
	v_pk_mul_f32 v[0:1], v[148:149], v[64:65] op_sel_hi:[0,1]
	v_pk_mul_f32 v[4:5], v[2:3], v[0:1]
	ds_read_b128 v[0:3], v104 offset:32
	s_waitcnt lgkmcnt(1)
	v_mfma_f32_32x32x16_bf16 v[64:79], v[8:11], v[82:85], 0
	v_cvt_pk_bf16_f32 v137, v4, v5
	v_mul_f32_e64 v4, v148, v100
	v_mul_f32_e64 v5, v148, v101
	s_waitcnt vmcnt(6)
; #define LAS __attribute__((address_space(3)))
; __device__ __forceinline__ void attn_item(const Params& P, int slice, int item, LAS unsigned char* lds) {
;     ...
;   f32x16 sc[5];
; #pragma unroll
;   for (int kt = 0; kt < 5; ++kt) {
; #pragma unroll
;     for (int i = 0; i < 16; ++i) sc[kt][i] = 0.f;
;     const LAS unsigned char* kp = img + (32 * wq + 32 * kt + qn) * KROW + 16 * h;
; #pragma unroll
;     for (int ks = 0; ks < 8; ++ks) { const bf16x8 a = *(const LAS bf16x8*)(kp + 32 * ks); sc[kt] = __builtin_amdgcn_mfma_f32_32x32x16_bf16(a, Qf[ks], sc[kt], 0, 0, 0); }
;   }
	v_mul_f32_e64 v4, v108, v4
	v_mul_f32_e64 v5, v109, v5
	v_cvt_pk_bf16_f32 v138, v4, v5
	v_pk_mul_f32 v[4:5], v[148:149], v[62:63] op_sel_hi:[0,1]
	v_pk_mul_f32 v[8:9], v[110:111], v[4:5]
	ds_read_b128 v[4:7], v104 offset:64
	s_waitcnt lgkmcnt(1)
	v_mfma_f32_32x32x16_bf16 v[64:79], v[0:3], v[86:89], v[64:79]
	v_mul_f32_e64 v0, v148, v60
	v_mul_f32_e64 v1, v148, v61
	s_waitcnt vmcnt(4)
	v_mul_f32_e64 v0, v116, v0
	v_mul_f32_e64 v1, v117, v1
	v_cvt_pk_bf16_f32 v139, v8, v9
	v_cvt_pk_bf16_f32 v108, v0, v1
	v_pk_mul_f32 v[0:1], v[148:149], v[58:59] op_sel_hi:[0,1]
	v_pk_mul_f32 v[8:9], v[118:119], v[0:1]
	ds_read_b128 v[0:3], v104 offset:96
	s_waitcnt lgkmcnt(1)
	v_mfma_f32_32x32x16_bf16 v[64:79], v[4:7], v[90:93], v[64:79]
	v_mul_f32_e64 v4, v148, v54
	v_mul_f32_e64 v5, v148, v55
	v_mul_f32_e64 v4, v112, v4
	v_mul_f32_e64 v5, v113, v5
	v_cvt_pk_bf16_f32 v109, v8, v9
	v_cvt_pk_bf16_f32 v110, v4, v5
	v_pk_mul_f32 v[4:5], v[148:149], v[50:51] op_sel_hi:[0,1]
	v_pk_mul_f32 v[8:9], v[114:115], v[4:5]
	ds_read_b128 v[4:7], v104 offset:128
	s_waitcnt lgkmcnt(1)
	v_mfma_f32_32x32x16_bf16 v[64:79], v[0:3], v[94:97], v[64:79]
	v_mul_f32_e64 v0, v148, v44
	v_mul_f32_e64 v1, v148, v45
	s_waitcnt vmcnt(2)
	v_mul_f32_e64 v0, v124, v0
	v_mul_f32_e64 v1, v125, v1
	v_cvt_pk_bf16_f32 v111, v8, v9
	v_cvt_pk_bf16_f32 v112, v0, v1
	v_pk_mul_f32 v[0:1], v[148:149], v[42:43] op_sel_hi:[0,1]
	v_pk_mul_f32 v[8:9], v[126:127], v[0:1]
	ds_read_b128 v[0:3], v104 offset:160
	s_waitcnt lgkmcnt(1)
	v_mfma_f32_32x32x16_bf16 v[64:79], v[4:7], v[136:139], v[64:79]
	v_mul_f32_e64 v4, v148, v40
	v_mul_f32_e64 v5, v148, v41
	v_mul_f32_e64 v4, v120, v4
	v_mul_f32_e64 v5, v121, v5
	v_cvt_pk_bf16_f32 v113, v8, v9
	v_cvt_pk_bf16_f32 v114, v4, v5
	v_pk_mul_f32 v[4:5], v[148:149], v[38:39] op_sel_hi:[0,1]
	v_pk_mul_f32 v[8:9], v[122:123], v[4:5]
	ds_read_b128 v[4:7], v104 offset:192
	s_waitcnt lgkmcnt(1)
	v_mfma_f32_32x32x16_bf16 v[64:79], v[0:3], v[108:111], v[64:79]
	v_mul_f32_e64 v0, v148, v56
	v_mul_f32_e64 v1, v148, v57
	s_waitcnt vmcnt(0)
	v_mul_f32_e64 v0, v132, v0
	v_mul_f32_e64 v1, v133, v1
	v_cvt_pk_bf16_f32 v115, v8, v9
	v_cvt_pk_bf16_f32 v116, v0, v1
	v_pk_mul_f32 v[0:1], v[148:149], v[52:53] op_sel_hi:[0,1]
	v_pk_mul_f32 v[8:9], v[134:135], v[0:1]
	ds_read_b128 v[0:3], v104 offset:224
	s_waitcnt lgkmcnt(1)
	v_mfma_f32_32x32x16_bf16 v[64:79], v[4:7], v[112:115], v[64:79]
	v_mul_f32_e64 v4, v148, v48
	v_mul_f32_e64 v5, v148, v49
	v_mul_f32_e64 v4, v128, v4
	v_mul_f32_e64 v5, v129, v5
	v_cvt_pk_bf16_f32 v117, v8, v9
	v_cvt_pk_bf16_f32 v118, v4, v5
	v_pk_mul_f32 v[4:5], v[148:149], v[46:47] op_sel_hi:[0,1]
	v_pk_mul_f32 v[4:5], v[130:131], v[4:5]
	s_nop 0
	v_cvt_pk_bf16_f32 v119, v4, v5
	s_waitcnt lgkmcnt(0)
	s_nop 0
	v_mfma_f32_32x32x16_bf16 v[64:79], v[0:3], v[116:119], v[64:79]
	ds_read_b128 v[0:3], v104 offset:8704
	ds_read_b128 v[4:7], v104 offset:8736
	s_waitcnt lgkmcnt(1)
	v_mfma_f32_32x32x16_bf16 v[48:63], v[0:3], v[82:85], 0
	s_waitcnt lgkmcnt(0)
	v_mfma_f32_32x32x16_bf16 v[48:63], v[4:7], v[86:89], v[48:63]
	ds_read_b128 v[0:3], v104 offset:8768
	ds_read_b128 v[4:7], v104 offset:8800
	s_waitcnt lgkmcnt(1)
	v_mfma_f32_32x32x16_bf16 v[48:63], v[0:3], v[90:93], v[48:63]
	s_waitcnt lgkmcnt(0)
	v_mfma_f32_32x32x16_bf16 v[48:63], v[4:7], v[94:97], v[48:63]
	ds_read_b128 v[0:3], v104 offset:8832
	ds_read_b128 v[4:7], v104 offset:8864
	s_waitcnt lgkmcnt(1)
	v_mfma_f32_32x32x16_bf16 v[48:63], v[0:3], v[136:139], v[48:63]
	s_waitcnt lgkmcnt(0)
	v_mfma_f32_32x32x16_bf16 v[48:63], v[4:7], v[108:111], v[48:63]
	ds_read_b128 v[0:3], v104 offset:8896
	ds_read_b128 v[4:7], v104 offset:8928
	s_waitcnt lgkmcnt(1)
	v_mfma_f32_32x32x16_bf16 v[48:63], v[0:3], v[112:115], v[48:63]
	s_waitcnt lgkmcnt(0)
	v_mfma_f32_32x32x16_bf16 v[48:63], v[4:7], v[116:119], v[48:63]
	ds_read_b128 v[0:3], v104 offset:17408
	ds_read_b128 v[4:7], v104 offset:17440
	s_waitcnt lgkmcnt(1)
	v_mfma_f32_32x32x16_bf16 v[32:47], v[0:3], v[82:85], 0
	s_waitcnt lgkmcnt(0)
	v_mfma_f32_32x32x16_bf16 v[32:47], v[4:7], v[86:89], v[32:47]
	ds_read_b128 v[0:3], v104 offset:17472
	ds_read_b128 v[4:7], v104 offset:17504
	s_waitcnt lgkmcnt(1)
	v_mfma_f32_32x32x16_bf16 v[32:47], v[0:3], v[90:93], v[32:47]
	s_waitcnt lgkmcnt(0)
	v_mfma_f32_32x32x16_bf16 v[32:47], v[4:7], v[94:97], v[32:47]
	ds_read_b128 v[0:3], v104 offset:17536
	ds_read_b128 v[4:7], v104 offset:17568
	s_waitcnt lgkmcnt(1)
	v_mfma_f32_32x32x16_bf16 v[32:47], v[0:3], v[136:139], v[32:47]
	s_waitcnt lgkmcnt(0)
	v_mfma_f32_32x32x16_bf16 v[32:47], v[4:7], v[108:111], v[32:47]
	ds_read_b128 v[0:3], v104 offset:17600
	ds_read_b128 v[4:7], v104 offset:17632
	s_waitcnt lgkmcnt(1)
	v_mfma_f32_32x32x16_bf16 v[32:47], v[0:3], v[112:115], v[32:47]
	s_waitcnt lgkmcnt(0)
	v_mfma_f32_32x32x16_bf16 v[32:47], v[4:7], v[116:119], v[32:47]
	ds_read_b128 v[0:3], v104 offset:26112
	ds_read_b128 v[4:7], v104 offset:26144
	s_waitcnt lgkmcnt(1)
	v_mfma_f32_32x32x16_bf16 v[16:31], v[0:3], v[82:85], 0
	s_waitcnt lgkmcnt(0)
	v_mfma_f32_32x32x16_bf16 v[16:31], v[4:7], v[86:89], v[16:31]
	ds_read_b128 v[0:3], v104 offset:26176
	ds_read_b128 v[4:7], v104 offset:26208
	s_waitcnt lgkmcnt(1)
	v_mfma_f32_32x32x16_bf16 v[16:31], v[0:3], v[90:93], v[16:31]
	s_waitcnt lgkmcnt(0)
	v_mfma_f32_32x32x16_bf16 v[16:31], v[4:7], v[94:97], v[16:31]
	ds_read_b128 v[0:3], v104 offset:26240
	ds_read_b128 v[4:7], v104 offset:26272
	s_waitcnt lgkmcnt(1)
	v_mfma_f32_32x32x16_bf16 v[16:31], v[0:3], v[136:139], v[16:31]
	s_waitcnt lgkmcnt(0)
	v_mfma_f32_32x32x16_bf16 v[16:31], v[4:7], v[108:111], v[16:31]
	ds_read_b128 v[0:3], v104 offset:26304
	ds_read_b128 v[4:7], v104 offset:26336
	s_waitcnt lgkmcnt(1)
; #define LAS __attribute__((address_space(3)))
; __device__ __forceinline__ void attn_item(const Params& P, int slice, int item, LAS unsigned char* lds) {
;     ...
;     for (int ks = 0; ks < 8; ++ks) { const bf16x8 a = *(const LAS bf16x8*)(kp + 32 * ks); sc[kt] = __builtin_amdgcn_mfma_f32_32x32x16_bf16(a, Qf[ks], sc[kt], 0, 0, 0); }
;   }
;   float mx = -3.0e38f;
; #pragma unroll
;   for (int kt = 0; kt < 5; ++kt)
; #pragma unroll
;     for (int i = 0; i < 16; ++i) {
;       const int keyl = 32 * kt + (i & 3) + 8 * (i >> 2) + 4 * h; const int delta = keyl - 64 - qn; const int km = m0 - 64 + 32 * wq + keyl;
;       const bool valid = (delta >= -64) && (delta <= 64) && (km >= 0) && (km < M);
;       int bi = delta + 64; bi = bi < 0 ? 0 : (bi > 128 ? 128 : bi);
;       const float sv = valid ? sc[kt][i] + bl[bi] : -1e30f;
;       sc[kt][i] = sv; mx = fmaxf(mx, sv);
;     }
	v_mfma_f32_32x32x16_bf16 v[16:31], v[0:3], v[112:115], v[16:31]
	ds_read_b128 v[0:3], v104 offset:34816
	ds_read_b128 v[120:123], v104 offset:34848
	s_waitcnt lgkmcnt(2)
	v_mfma_f32_32x32x16_bf16 v[16:31], v[4:7], v[116:119], v[16:31]
	s_waitcnt lgkmcnt(1)
	v_mfma_f32_32x32x16_bf16 v[0:15], v[0:3], v[82:85], 0
	s_waitcnt lgkmcnt(0)
	v_mfma_f32_32x32x16_bf16 v[0:15], v[120:123], v[86:89], v[0:15]
	ds_read_b128 v[82:85], v104 offset:34880
	ds_read_b128 v[86:89], v104 offset:34912
	s_waitcnt lgkmcnt(1)
	v_mfma_f32_32x32x16_bf16 v[0:15], v[82:85], v[90:93], v[0:15]
	s_waitcnt lgkmcnt(0)
	v_mfma_f32_32x32x16_bf16 v[0:15], v[86:89], v[94:97], v[0:15]
	ds_read_b128 v[82:85], v104 offset:34944
	ds_read_b128 v[86:89], v104 offset:34976
	s_waitcnt lgkmcnt(1)
	v_mfma_f32_32x32x16_bf16 v[0:15], v[82:85], v[136:139], v[0:15]
	s_waitcnt lgkmcnt(0)
	v_mfma_f32_32x32x16_bf16 v[0:15], v[86:89], v[108:111], v[0:15]
	ds_read_b128 v[82:85], v104 offset:35008
	ds_read_b128 v[86:89], v104 offset:35040
	s_waitcnt lgkmcnt(1)
	v_mfma_f32_32x32x16_bf16 v[0:15], v[82:85], v[112:115], v[0:15]
	v_sub_u32_e32 v84, v168, v102
	v_or_b32_e32 v82, s71, v168
	v_cmp_gt_u32_e32 vcc, s0, v84
	s_cselect_b64 s[0:1], -1, 0
	s_and_b64 s[74:75], vcc, s[0:1]
	v_cmp_gt_i32_e32 vcc, s68, v82
	s_and_b64 s[74:75], s[74:75], vcc
	s_waitcnt lgkmcnt(0)
	v_mfma_f32_32x32x16_bf16 v[0:15], v[86:89], v[116:119], v[0:15]
	v_mov_b32_e32 v82, 0xf149f2ca
	v_mov_b32_e32 v83, 0xf149f2ca
	v_lshl_add_u32 v171, v84, 2, s76
	ds_read_b32 v172, v171
	ds_read_b32 v173, v171 offset:4
	ds_read_b32 v174, v171 offset:8
	ds_read_b32 v175, v171 offset:12
	ds_read_b32 v176, v171 offset:32
	ds_read_b32 v177, v171 offset:36
	ds_read_b32 v178, v171 offset:40
	ds_read_b32 v179, v171 offset:44
	ds_read_b32 v180, v171 offset:64
	ds_read_b32 v181, v171 offset:68
	ds_read_b32 v182, v171 offset:72
	ds_read_b32 v183, v171 offset:76
	ds_read_b32 v184, v171 offset:96
	ds_read_b32 v185, v171 offset:100
	ds_read_b32 v186, v171 offset:104
	ds_read_b32 v187, v171 offset:108
	ds_read_b32 v188, v171 offset:128
	ds_read_b32 v189, v171 offset:132
	ds_read_b32 v190, v171 offset:136
	ds_read_b32 v191, v171 offset:140
	ds_read_b32 v192, v171 offset:160
	ds_read_b32 v193, v171 offset:164
	ds_read_b32 v194, v171 offset:168
	ds_read_b32 v195, v171 offset:172
	ds_read_b32 v196, v171 offset:192
	ds_read_b32 v197, v171 offset:196
	ds_read_b32 v198, v171 offset:200
	ds_read_b32 v199, v171 offset:204
	ds_read_b32 v200, v171 offset:224
	ds_read_b32 v201, v171 offset:228
	ds_read_b32 v202, v171 offset:232
	ds_read_b32 v203, v171 offset:236
	ds_read_b32 v204, v171 offset:256
	ds_read_b32 v205, v171 offset:260
	ds_read_b32 v206, v171 offset:264
	ds_read_b32 v207, v171 offset:268
	ds_read_b32 v208, v171 offset:288
	ds_read_b32 v209, v171 offset:292
	ds_read_b32 v210, v171 offset:296
	ds_read_b32 v211, v171 offset:300
	s_waitcnt lgkmcnt(15)
	v_add_f32_e32 v212, v64, v172
	v_cndmask_b32_e64 v83, v83, v212, s[74:75]
.LBB0_660:
	v_or_b32_e32 v64, 1, v168
	v_sub_u32_e32 v85, v64, v102
	s_movk_i32 s31, 0x81
	v_or_b32_e32 v64, s71, v64
	v_cmp_gt_u32_e32 vcc, s31, v85
	s_and_b64 s[74:75], vcc, s[0:1]
	v_cmp_gt_i32_e32 vcc, s68, v64
	s_and_b64 s[74:75], s[74:75], vcc
	s_waitcnt lgkmcnt(15)
	v_add_f32_e32 v212, v65, v173
	v_cndmask_b32_e64 v82, v82, v212, s[74:75]
.LBB0_662:
	v_or_b32_e32 v64, 2, v168
	v_sub_u32_e32 v65, v64, v102
	v_or_b32_e32 v64, s71, v64
	v_cmp_gt_u32_e32 vcc, s31, v65
	s_and_b64 s[74:75], vcc, s[0:1]
	v_cmp_gt_i32_e32 vcc, s68, v64
	s_and_b64 s[74:75], s[74:75], vcc
	v_mov_b32_e32 v64, 0xf149f2ca
	v_mov_b32_e32 v65, 0xf149f2ca
	s_waitcnt lgkmcnt(15)
	v_add_f32_e32 v212, v66, v174
	v_cndmask_b32_e64 v65, v65, v212, s[74:75]
.LBB0_664:
	v_or_b32_e32 v66, 3, v168
	v_sub_u32_e32 v85, v66, v102
	v_or_b32_e32 v66, s71, v66
	v_cmp_gt_u32_e32 vcc, s31, v85
	s_and_b64 s[74:75], vcc, s[0:1]
	v_cmp_gt_i32_e32 vcc, s68, v66
	s_and_b64 s[74:75], s[74:75], vcc
	s_waitcnt lgkmcnt(15)
	v_add_f32_e32 v212, v67, v175
	v_cndmask_b32_e64 v64, v64, v212, s[74:75]
.LBB0_666:
	v_or_b32_e32 v66, 8, v168
	v_sub_u32_e32 v67, v66, v102
	v_or_b32_e32 v66, s71, v66
	v_cmp_gt_u32_e32 vcc, s31, v67
	s_and_b64 s[74:75], vcc, s[0:1]
	v_cmp_gt_i32_e32 vcc, s68, v66
	s_and_b64 s[74:75], s[74:75], vcc
	v_mov_b32_e32 v66, 0xf149f2ca
	v_mov_b32_e32 v67, 0xf149f2ca
	s_waitcnt lgkmcnt(15)
	v_add_f32_e32 v212, v68, v176
	v_cndmask_b32_e64 v67, v67, v212, s[74:75]
.LBB0_668:
	v_or_b32_e32 v68, 9, v168
	v_sub_u32_e32 v85, v68, v102
	v_or_b32_e32 v68, s71, v68
	v_cmp_gt_u32_e32 vcc, s31, v85
	s_and_b64 s[74:75], vcc, s[0:1]
	v_cmp_gt_i32_e32 vcc, s68, v68
	s_and_b64 s[74:75], s[74:75], vcc
	s_waitcnt lgkmcnt(15)
	v_add_f32_e32 v212, v69, v177
	v_cndmask_b32_e64 v66, v66, v212, s[74:75]
.LBB0_670:
	v_or_b32_e32 v68, 10, v168
	v_sub_u32_e32 v69, v68, v102
	v_or_b32_e32 v68, s71, v68
	v_cmp_gt_u32_e32 vcc, s31, v69
	s_and_b64 s[74:75], vcc, s[0:1]
	v_cmp_gt_i32_e32 vcc, s68, v68
	s_and_b64 s[74:75], s[74:75], vcc
	v_mov_b32_e32 v68, 0xf149f2ca
	v_mov_b32_e32 v69, 0xf149f2ca
	s_waitcnt lgkmcnt(15)
	v_add_f32_e32 v212, v70, v178
	v_cndmask_b32_e64 v69, v69, v212, s[74:75]
.LBB0_672:
	v_or_b32_e32 v70, 11, v168
	v_sub_u32_e32 v85, v70, v102
	v_or_b32_e32 v70, s71, v70
	v_cmp_gt_u32_e32 vcc, s31, v85
	s_and_b64 s[74:75], vcc, s[0:1]
	v_cmp_gt_i32_e32 vcc, s68, v70
	s_and_b64 s[74:75], s[74:75], vcc
	s_waitcnt lgkmcnt(15)
	v_add_f32_e32 v212, v71, v179
	v_cndmask_b32_e64 v68, v68, v212, s[74:75]
; __device__ __forceinline__ void attn_item(const Params& P, int slice, int item, LAS unsigned char* lds) {
;     ...
;   float mx = -3.0e38f;
; #pragma unroll
;   for (int kt = 0; kt < 5; ++kt)
; #pragma unroll
;     for (int i = 0; i < 16; ++i) {
;       const int keyl = 32 * kt + (i & 3) + 8 * (i >> 2) + 4 * h; const int delta = keyl - 64 - qn; const int km = m0 - 64 + 32 * wq + keyl;
;       const bool valid = (delta >= -64) && (delta <= 64) && (km >= 0) && (km < M);
;       int bi = delta + 64; bi = bi < 0 ? 0 : (bi > 128 ? 128 : bi);
;       const float sv = valid ? sc[kt][i] + bl[bi] : -1e30f;
;       sc[kt][i] = sv; mx = fmaxf(mx, sv);
;     }
.LBB0_674:
	v_or_b32_e32 v70, 16, v168
	v_sub_u32_e32 v71, v70, v102
	v_or_b32_e32 v70, s71, v70
	v_cmp_gt_u32_e32 vcc, s31, v71
	s_and_b64 s[74:75], vcc, s[0:1]
	v_cmp_gt_i32_e32 vcc, s68, v70
	s_and_b64 s[74:75], s[74:75], vcc
	v_mov_b32_e32 v70, 0xf149f2ca
	v_mov_b32_e32 v71, 0xf149f2ca
	s_waitcnt lgkmcnt(15)
	v_add_f32_e32 v212, v72, v180
	v_cndmask_b32_e64 v71, v71, v212, s[74:75]
.LBB0_676:
	v_or_b32_e32 v72, 17, v168
	v_sub_u32_e32 v85, v72, v102
	v_or_b32_e32 v72, s71, v72
	v_cmp_gt_u32_e32 vcc, s31, v85
	s_and_b64 s[74:75], vcc, s[0:1]
	v_cmp_gt_i32_e32 vcc, s68, v72
	s_and_b64 s[74:75], s[74:75], vcc
	s_waitcnt lgkmcnt(15)
	v_add_f32_e32 v212, v73, v181
	v_cndmask_b32_e64 v70, v70, v212, s[74:75]
.LBB0_678:
	v_or_b32_e32 v72, 18, v168
	v_sub_u32_e32 v73, v72, v102
	v_or_b32_e32 v72, s71, v72
	v_cmp_gt_u32_e32 vcc, s31, v73
	s_and_b64 s[74:75], vcc, s[0:1]
	v_cmp_gt_i32_e32 vcc, s68, v72
	s_and_b64 s[74:75], s[74:75], vcc
	v_mov_b32_e32 v72, 0xf149f2ca
	v_mov_b32_e32 v73, 0xf149f2ca
	s_waitcnt lgkmcnt(15)
	v_add_f32_e32 v212, v74, v182
	v_cndmask_b32_e64 v73, v73, v212, s[74:75]
.LBB0_680:
	v_or_b32_e32 v74, 19, v168
	v_sub_u32_e32 v85, v74, v102
	v_or_b32_e32 v74, s71, v74
	v_cmp_gt_u32_e32 vcc, s31, v85
	s_and_b64 s[74:75], vcc, s[0:1]
	v_cmp_gt_i32_e32 vcc, s68, v74
	s_and_b64 s[74:75], s[74:75], vcc
	s_waitcnt lgkmcnt(15)
	v_add_f32_e32 v212, v75, v183
	v_cndmask_b32_e64 v72, v72, v212, s[74:75]
.LBB0_682:
	v_or_b32_e32 v74, 24, v168
	v_sub_u32_e32 v75, v74, v102
	v_or_b32_e32 v74, s71, v74
	v_cmp_gt_u32_e32 vcc, s31, v75
	s_and_b64 s[74:75], vcc, s[0:1]
	v_cmp_gt_i32_e32 vcc, s68, v74
	s_and_b64 s[74:75], s[74:75], vcc
	v_mov_b32_e32 v74, 0xf149f2ca
	v_mov_b32_e32 v75, 0xf149f2ca
	s_waitcnt lgkmcnt(15)
	v_add_f32_e32 v212, v76, v184
	v_cndmask_b32_e64 v75, v75, v212, s[74:75]
.LBB0_684:
	v_or_b32_e32 v76, 25, v168
	v_sub_u32_e32 v85, v76, v102
	v_or_b32_e32 v76, s71, v76
	v_cmp_gt_u32_e32 vcc, s31, v85
	s_and_b64 s[74:75], vcc, s[0:1]
	v_cmp_gt_i32_e32 vcc, s68, v76
	s_and_b64 s[74:75], s[74:75], vcc
	s_waitcnt lgkmcnt(15)
	v_add_f32_e32 v212, v77, v185
	v_cndmask_b32_e64 v74, v74, v212, s[74:75]
.LBB0_686:
	v_or_b32_e32 v76, 26, v168
	v_sub_u32_e32 v77, v76, v102
	v_or_b32_e32 v76, s71, v76
	v_cmp_gt_u32_e32 vcc, s31, v77
	s_and_b64 s[74:75], vcc, s[0:1]
	v_cmp_gt_i32_e32 vcc, s68, v76
	s_and_b64 s[74:75], s[74:75], vcc
	v_mov_b32_e32 v86, 0xf149f2ca
	v_mov_b32_e32 v87, 0xf149f2ca
	s_waitcnt lgkmcnt(15)
	v_add_f32_e32 v212, v78, v186
	v_cndmask_b32_e64 v87, v87, v212, s[74:75]
.LBB0_688:
	v_or_b32_e32 v76, 27, v168
	v_sub_u32_e32 v77, v76, v102
	v_or_b32_e32 v76, s71, v76
	v_cmp_gt_u32_e32 vcc, s31, v77
	s_and_b64 s[0:1], vcc, s[0:1]
	v_cmp_gt_i32_e32 vcc, s68, v76
	s_and_b64 s[74:75], s[0:1], vcc
	s_waitcnt lgkmcnt(15)
	v_add_f32_e32 v212, v79, v187
	v_cndmask_b32_e64 v86, v86, v212, s[74:75]
.LBB0_690:
	v_or_b32_e32 v76, 32, v168
	v_add_u32_e32 v76, s71, v76
	v_cmp_lt_i32_e32 vcc, -1, v76
	v_cmp_gt_i32_e64 s[0:1], s68, v76
	s_and_b64 s[74:75], vcc, s[0:1]
	v_mov_b32_e32 v88, 0xf149f2ca
	v_mov_b32_e32 v89, 0xf149f2ca
	s_waitcnt lgkmcnt(15)
	v_add_f32_e32 v212, v48, v188
	v_cndmask_b32_e64 v89, v89, v212, s[74:75]
.LBB0_692:
	v_or_b32_e32 v48, 33, v168
	v_add_u32_e32 v48, s71, v48
	v_cmp_lt_i32_e32 vcc, -1, v48
	v_cmp_gt_i32_e64 s[0:1], s68, v48
	s_and_b64 s[74:75], vcc, s[0:1]
	s_waitcnt lgkmcnt(15)
	v_add_f32_e32 v212, v49, v189
	v_cndmask_b32_e64 v88, v88, v212, s[74:75]
.LBB0_694:
	v_or_b32_e32 v48, 34, v168
	v_add_u32_e32 v48, s71, v48
	v_cmp_lt_i32_e32 vcc, -1, v48
	v_cmp_gt_i32_e64 s[0:1], s68, v48
	s_and_b64 s[74:75], vcc, s[0:1]
	v_mov_b32_e32 v48, 0xf149f2ca
	v_mov_b32_e32 v49, 0xf149f2ca
	s_waitcnt lgkmcnt(15)
	v_add_f32_e32 v212, v50, v190
	v_cndmask_b32_e64 v49, v49, v212, s[74:75]
.LBB0_696:
	v_or_b32_e32 v50, 35, v168
	v_add_u32_e32 v50, s71, v50
	v_cmp_lt_i32_e32 vcc, -1, v50
	v_cmp_gt_i32_e64 s[0:1], s68, v50
	s_and_b64 s[74:75], vcc, s[0:1]
	s_waitcnt lgkmcnt(15)
	v_add_f32_e32 v212, v51, v191
	v_cndmask_b32_e64 v48, v48, v212, s[74:75]
.LBB0_698:
	v_or_b32_e32 v50, 40, v168
	v_add_u32_e32 v50, s71, v50
	v_cmp_lt_i32_e32 vcc, -1, v50
	v_cmp_gt_i32_e64 s[0:1], s68, v50
	s_and_b64 s[74:75], vcc, s[0:1]
	v_mov_b32_e32 v50, 0xf149f2ca
	v_mov_b32_e32 v51, 0xf149f2ca
	s_waitcnt lgkmcnt(15)
	v_add_f32_e32 v212, v52, v192
	v_cndmask_b32_e64 v51, v51, v212, s[74:75]
.LBB0_700:
	v_or_b32_e32 v52, 41, v168
	v_add_u32_e32 v52, s71, v52
	v_cmp_lt_i32_e32 vcc, -1, v52
	v_cmp_gt_i32_e64 s[0:1], s68, v52
	s_and_b64 s[74:75], vcc, s[0:1]
	s_waitcnt lgkmcnt(15)
	v_add_f32_e32 v212, v53, v193
	v_cndmask_b32_e64 v50, v50, v212, s[74:75]
.LBB0_702:
	v_or_b32_e32 v52, 42, v168
	v_add_u32_e32 v52, s71, v52
	v_cmp_lt_i32_e32 vcc, -1, v52
	v_cmp_gt_i32_e64 s[0:1], s68, v52
	s_and_b64 s[74:75], vcc, s[0:1]
	v_mov_b32_e32 v52, 0xf149f2ca
	v_mov_b32_e32 v53, 0xf149f2ca
	s_waitcnt lgkmcnt(15)
	v_add_f32_e32 v212, v54, v194
	v_cndmask_b32_e64 v53, v53, v212, s[74:75]
.LBB0_704:
	v_or_b32_e32 v54, 43, v168
	v_add_u32_e32 v54, s71, v54
	v_cmp_lt_i32_e32 vcc, -1, v54
	v_cmp_gt_i32_e64 s[0:1], s68, v54
	s_and_b64 s[74:75], vcc, s[0:1]
	s_waitcnt lgkmcnt(15)
	v_add_f32_e32 v212, v55, v195
	v_cndmask_b32_e64 v52, v52, v212, s[74:75]
.LBB0_706:
	v_or_b32_e32 v54, 48, v168
	v_add_u32_e32 v54, s71, v54
	v_cmp_lt_i32_e32 vcc, -1, v54
	v_cmp_gt_i32_e64 s[0:1], s68, v54
	s_and_b64 s[74:75], vcc, s[0:1]
	v_mov_b32_e32 v54, 0xf149f2ca
	v_mov_b32_e32 v55, 0xf149f2ca
	s_waitcnt lgkmcnt(15)
	v_add_f32_e32 v212, v56, v196
	v_cndmask_b32_e64 v55, v55, v212, s[74:75]
; __device__ __forceinline__ void attn_item(const Params& P, int slice, int item, LAS unsigned char* lds) {
;     ...
;   float mx = -3.0e38f;
; #pragma unroll
;   for (int kt = 0; kt < 5; ++kt)
; #pragma unroll
;     for (int i = 0; i < 16; ++i) {
;       const int keyl = 32 * kt + (i & 3) + 8 * (i >> 2) + 4 * h; const int delta = keyl - 64 - qn; const int km = m0 - 64 + 32 * wq + keyl;
;       const bool valid = (delta >= -64) && (delta <= 64) && (km >= 0) && (km < M);
;       int bi = delta + 64; bi = bi < 0 ? 0 : (bi > 128 ? 128 : bi);
;       const float sv = valid ? sc[kt][i] + bl[bi] : -1e30f;
;       sc[kt][i] = sv; mx = fmaxf(mx, sv);
;     }
.LBB0_708:
	v_or_b32_e32 v56, 49, v168
	v_add_u32_e32 v56, s71, v56
	v_cmp_lt_i32_e32 vcc, -1, v56
	v_cmp_gt_i32_e64 s[0:1], s68, v56
	s_and_b64 s[74:75], vcc, s[0:1]
	s_waitcnt lgkmcnt(14)
	v_add_f32_e32 v212, v57, v197
	v_cndmask_b32_e64 v54, v54, v212, s[74:75]
.LBB0_710:
	v_or_b32_e32 v56, 50, v168
	v_add_u32_e32 v56, s71, v56
	v_cmp_lt_i32_e32 vcc, -1, v56
	v_cmp_gt_i32_e64 s[0:1], s68, v56
	s_and_b64 s[74:75], vcc, s[0:1]
	v_mov_b32_e32 v56, 0xf149f2ca
	v_mov_b32_e32 v57, 0xf149f2ca
	s_waitcnt lgkmcnt(13)
	v_add_f32_e32 v212, v58, v198
	v_cndmask_b32_e64 v57, v57, v212, s[74:75]
.LBB0_712:
	v_or_b32_e32 v58, 51, v168
	v_add_u32_e32 v58, s71, v58
	v_cmp_lt_i32_e32 vcc, -1, v58
	v_cmp_gt_i32_e64 s[0:1], s68, v58
	s_and_b64 s[74:75], vcc, s[0:1]
	s_waitcnt lgkmcnt(12)
	v_add_f32_e32 v212, v59, v199
	v_cndmask_b32_e64 v56, v56, v212, s[74:75]
.LBB0_714:
	v_or_b32_e32 v58, 56, v168
	v_add_u32_e32 v58, s71, v58
	v_cmp_lt_i32_e32 vcc, -1, v58
	v_cmp_gt_i32_e64 s[0:1], s68, v58
	s_and_b64 s[74:75], vcc, s[0:1]
	v_mov_b32_e32 v58, 0xf149f2ca
	v_mov_b32_e32 v59, 0xf149f2ca
	s_waitcnt lgkmcnt(11)
	v_add_f32_e32 v212, v60, v200
	v_cndmask_b32_e64 v59, v59, v212, s[74:75]
.LBB0_716:
	v_or_b32_e32 v60, 57, v168
	v_add_u32_e32 v60, s71, v60
	v_cmp_lt_i32_e32 vcc, -1, v60
	v_cmp_gt_i32_e64 s[0:1], s68, v60
	s_and_b64 s[74:75], vcc, s[0:1]
	s_waitcnt lgkmcnt(10)
	v_add_f32_e32 v212, v61, v201
	v_cndmask_b32_e64 v58, v58, v212, s[74:75]
.LBB0_718:
	v_or_b32_e32 v60, 58, v168
	v_add_u32_e32 v60, s71, v60
	v_cmp_lt_i32_e32 vcc, -1, v60
	v_cmp_gt_i32_e64 s[0:1], s68, v60
	s_and_b64 s[74:75], vcc, s[0:1]
	v_mov_b32_e32 v60, 0xf149f2ca
	v_mov_b32_e32 v61, 0xf149f2ca
	s_waitcnt lgkmcnt(9)
	v_add_f32_e32 v212, v62, v202
	v_cndmask_b32_e64 v61, v61, v212, s[74:75]
.LBB0_720:
	v_or_b32_e32 v62, 59, v168
	v_add_u32_e32 v62, s71, v62
	v_cmp_lt_i32_e32 vcc, -1, v62
	v_cmp_gt_i32_e64 s[0:1], s68, v62
	s_and_b64 s[74:75], vcc, s[0:1]
	s_waitcnt lgkmcnt(8)
	v_add_f32_e32 v212, v63, v203
	v_cndmask_b32_e64 v60, v60, v212, s[74:75]
.LBB0_722:
	v_add3_u32 v62, s71, v168, 64
	v_cmp_gt_u32_e32 vcc, s68, v62
	v_mov_b32_e32 v62, 0xf149f2ca
	v_mov_b32_e32 v63, 0xf149f2ca
	s_waitcnt lgkmcnt(7)
	v_add_f32_e32 v212, v32, v204
	v_cndmask_b32_e64 v63, v63, v212, vcc
.LBB0_724:
	v_add_u32_e32 v76, s71, v168
	v_add_u32_e32 v32, 0x41, v76
	v_cmp_gt_u32_e32 vcc, s68, v32
	s_waitcnt lgkmcnt(6)
	v_add_f32_e32 v212, v33, v205
	v_cndmask_b32_e64 v62, v62, v212, vcc
.LBB0_726:
	v_add_u32_e32 v32, 0x42, v76
	v_cmp_gt_u32_e32 vcc, s68, v32
	v_mov_b32_e32 v32, 0xf149f2ca
	v_mov_b32_e32 v33, 0xf149f2ca
	s_waitcnt lgkmcnt(5)
	v_add_f32_e32 v212, v34, v206
	v_cndmask_b32_e64 v33, v33, v212, vcc
.LBB0_728:
	v_add_u32_e32 v34, 0x43, v76
	v_cmp_gt_u32_e32 vcc, s68, v34
	s_waitcnt lgkmcnt(4)
	v_add_f32_e32 v212, v35, v207
	v_cndmask_b32_e64 v32, v32, v212, vcc
.LBB0_730:
	v_add_u32_e32 v34, 0x48, v76
	v_cmp_gt_u32_e32 vcc, s68, v34
	v_mov_b32_e32 v34, 0xf149f2ca
	v_mov_b32_e32 v35, 0xf149f2ca
	s_waitcnt lgkmcnt(3)
	v_add_f32_e32 v212, v36, v208
	v_cndmask_b32_e64 v35, v35, v212, vcc
.LBB0_732:
	v_add_u32_e32 v36, 0x49, v76
	v_cmp_gt_u32_e32 vcc, s68, v36
	s_waitcnt lgkmcnt(2)
	v_add_f32_e32 v212, v37, v209
	v_cndmask_b32_e64 v34, v34, v212, vcc
.LBB0_734:
	v_add_u32_e32 v36, 0x4a, v76
	v_cmp_gt_u32_e32 vcc, s68, v36
	v_mov_b32_e32 v36, 0xf149f2ca
	v_mov_b32_e32 v37, 0xf149f2ca
	s_waitcnt lgkmcnt(1)
	v_add_f32_e32 v212, v38, v210
	v_cndmask_b32_e64 v37, v37, v212, vcc
.LBB0_736:
	v_add_u32_e32 v38, 0x4b, v76
	v_cmp_gt_u32_e32 vcc, s68, v38
	s_waitcnt lgkmcnt(0)
	v_add_f32_e32 v212, v39, v211
	v_cndmask_b32_e64 v36, v36, v212, vcc
.LBB0_738:
	v_lshl_add_u32 v171, v84, 2, s76
	ds_read_b32 v172, v171 offset:320
	ds_read_b32 v173, v171 offset:324
	ds_read_b32 v174, v171 offset:328
	ds_read_b32 v175, v171 offset:332
	ds_read_b32 v176, v171 offset:352
	ds_read_b32 v177, v171 offset:356
	ds_read_b32 v178, v171 offset:360
	ds_read_b32 v179, v171 offset:364
	ds_read_b32 v180, v171 offset:384
	ds_read_b32 v181, v171 offset:388
	ds_read_b32 v182, v171 offset:392
	ds_read_b32 v183, v171 offset:396
	ds_read_b32 v184, v171 offset:416
	ds_read_b32 v185, v171 offset:420
	ds_read_b32 v186, v171 offset:424
	ds_read_b32 v187, v171 offset:428
	ds_read_b32 v188, v171 offset:448
	ds_read_b32 v189, v171 offset:452
	ds_read_b32 v190, v171 offset:456
	ds_read_b32 v191, v171 offset:460
	ds_read_b32 v192, v171 offset:480
	ds_read_b32 v193, v171 offset:484
	ds_read_b32 v194, v171 offset:488
	ds_read_b32 v195, v171 offset:492
	ds_read_b32 v196, v171 offset:512
	ds_read_b32 v197, v171 offset:516
	ds_read_b32 v198, v171 offset:520
	ds_read_b32 v199, v171 offset:524
	ds_read_b32 v200, v171 offset:544
	ds_read_b32 v201, v171 offset:548
	ds_read_b32 v202, v171 offset:552
	ds_read_b32 v203, v171 offset:556
	ds_read_b32 v204, v171 offset:576
	ds_read_b32 v205, v171 offset:580
	ds_read_b32 v206, v171 offset:584
	ds_read_b32 v207, v171 offset:588
	ds_read_b32 v208, v171 offset:608
	ds_read_b32 v209, v171 offset:612
	ds_read_b32 v210, v171 offset:616
	ds_read_b32 v211, v171 offset:620
	v_add_u32_e32 v38, 0x50, v76
	v_cmp_gt_u32_e32 vcc, s68, v38
	v_mov_b32_e32 v38, 0xf149f2ca
	v_mov_b32_e32 v39, 0xf149f2ca
	s_waitcnt lgkmcnt(15)
	v_add_f32_e32 v212, v40, v172
	v_cndmask_b32_e64 v39, v39, v212, vcc
.LBB0_740:
	v_add_u32_e32 v40, 0x51, v76
	v_cmp_gt_u32_e32 vcc, s68, v40
	s_waitcnt lgkmcnt(15)
	v_add_f32_e32 v212, v41, v173
	v_cndmask_b32_e64 v38, v38, v212, vcc
.LBB0_742:
	v_add_u32_e32 v40, 0x52, v76
	v_cmp_gt_u32_e32 vcc, s68, v40
	v_mov_b32_e32 v40, 0xf149f2ca
	v_mov_b32_e32 v41, 0xf149f2ca
	s_waitcnt lgkmcnt(15)
	v_add_f32_e32 v212, v42, v174
	v_cndmask_b32_e64 v41, v41, v212, vcc
; __device__ __forceinline__ void attn_item(const Params& P, int slice, int item, LAS unsigned char* lds) {
;     ...
;   float mx = -3.0e38f;
; #pragma unroll
;   for (int kt = 0; kt < 5; ++kt)
; #pragma unroll
;     for (int i = 0; i < 16; ++i) {
;       const int keyl = 32 * kt + (i & 3) + 8 * (i >> 2) + 4 * h; const int delta = keyl - 64 - qn; const int km = m0 - 64 + 32 * wq + keyl;
;       const bool valid = (delta >= -64) && (delta <= 64) && (km >= 0) && (km < M);
;       int bi = delta + 64; bi = bi < 0 ? 0 : (bi > 128 ? 128 : bi);
;       const float sv = valid ? sc[kt][i] + bl[bi] : -1e30f;
;       sc[kt][i] = sv; mx = fmaxf(mx, sv);
;     }
.LBB0_744:
	v_add_u32_e32 v42, 0x53, v76
	v_cmp_gt_u32_e32 vcc, s68, v42
	s_waitcnt lgkmcnt(15)
	v_add_f32_e32 v212, v43, v175
	v_cndmask_b32_e64 v40, v40, v212, vcc
.LBB0_746:
	v_add_u32_e32 v42, 0x58, v76
	v_cmp_gt_u32_e32 vcc, s68, v42
	v_mov_b32_e32 v42, 0xf149f2ca
	v_mov_b32_e32 v43, 0xf149f2ca
	s_waitcnt lgkmcnt(15)
	v_add_f32_e32 v212, v44, v176
	v_cndmask_b32_e64 v43, v43, v212, vcc
.LBB0_748:
	v_add_u32_e32 v44, 0x59, v76
	v_cmp_gt_u32_e32 vcc, s68, v44
	s_waitcnt lgkmcnt(15)
	v_add_f32_e32 v212, v45, v177
	v_cndmask_b32_e64 v42, v42, v212, vcc
.LBB0_750:
	v_add_u32_e32 v44, 0x5a, v76
	v_cmp_gt_u32_e32 vcc, s68, v44
	v_mov_b32_e32 v44, 0xf149f2ca
	v_mov_b32_e32 v45, 0xf149f2ca
	s_waitcnt lgkmcnt(15)
	v_add_f32_e32 v212, v46, v178
	v_cndmask_b32_e64 v45, v45, v212, vcc
.LBB0_752:
	v_add_u32_e32 v46, 0x5b, v76
	v_cmp_gt_u32_e32 vcc, s68, v46
	s_waitcnt lgkmcnt(15)
	v_add_f32_e32 v212, v47, v179
	v_cndmask_b32_e64 v44, v44, v212, vcc
.LBB0_754:
	v_add_u32_e32 v46, 0x60, v76
	v_cmp_gt_u32_e32 vcc, s68, v46
	v_mov_b32_e32 v46, 0xf149f2ca
	v_mov_b32_e32 v47, 0xf149f2ca
	s_waitcnt lgkmcnt(15)
	v_add_f32_e32 v212, v16, v180
	v_cndmask_b32_e64 v47, v47, v212, vcc
.LBB0_756:
	v_add_u32_e32 v16, 0x61, v76
	v_cmp_gt_u32_e32 vcc, s68, v16
	s_waitcnt lgkmcnt(15)
	v_add_f32_e32 v212, v17, v181
	v_cndmask_b32_e64 v46, v46, v212, vcc
.LBB0_758:
	v_add_u32_e32 v16, 0x62, v76
	v_cmp_gt_u32_e32 vcc, s68, v16
	v_mov_b32_e32 v16, 0xf149f2ca
	v_mov_b32_e32 v17, 0xf149f2ca
	s_waitcnt lgkmcnt(15)
	v_add_f32_e32 v212, v18, v182
	v_cndmask_b32_e64 v17, v17, v212, vcc
.LBB0_760:
	v_add_u32_e32 v18, 0x63, v76
	v_cmp_gt_u32_e32 vcc, s68, v18
	s_waitcnt lgkmcnt(15)
	v_add_f32_e32 v212, v19, v183
	v_cndmask_b32_e64 v16, v16, v212, vcc
.LBB0_762:
	v_add_u32_e32 v18, 0x68, v76
	v_cmp_gt_u32_e32 vcc, s68, v18
	v_mov_b32_e32 v18, 0xf149f2ca
	v_mov_b32_e32 v19, 0xf149f2ca
	s_waitcnt lgkmcnt(15)
	v_add_f32_e32 v212, v20, v184
	v_cndmask_b32_e64 v19, v19, v212, vcc
.LBB0_764:
	v_add_u32_e32 v20, 0x69, v76
	v_cmp_gt_u32_e32 vcc, s68, v20
	s_waitcnt lgkmcnt(15)
	v_add_f32_e32 v212, v21, v185
	v_cndmask_b32_e64 v18, v18, v212, vcc
.LBB0_766:
	v_add_u32_e32 v20, 0x6a, v76
	v_cmp_gt_u32_e32 vcc, s68, v20
	v_mov_b32_e32 v20, 0xf149f2ca
	v_mov_b32_e32 v21, 0xf149f2ca
	s_waitcnt lgkmcnt(15)
	v_add_f32_e32 v212, v22, v186
	v_cndmask_b32_e64 v21, v21, v212, vcc
.LBB0_768:
	v_add_u32_e32 v22, 0x6b, v76
	v_cmp_gt_u32_e32 vcc, s68, v22
	s_waitcnt lgkmcnt(15)
	v_add_f32_e32 v212, v23, v187
	v_cndmask_b32_e64 v20, v20, v212, vcc
.LBB0_770:
	v_add_u32_e32 v22, 0x70, v76
	v_cmp_gt_u32_e32 vcc, s68, v22
	v_mov_b32_e32 v22, 0xf149f2ca
	v_mov_b32_e32 v23, 0xf149f2ca
	s_waitcnt lgkmcnt(15)
	v_add_f32_e32 v212, v24, v188
	v_cndmask_b32_e64 v23, v23, v212, vcc
.LBB0_772:
	v_add_u32_e32 v24, 0x71, v76
	v_cmp_gt_u32_e32 vcc, s68, v24
	s_waitcnt lgkmcnt(15)
	v_add_f32_e32 v212, v25, v189
	v_cndmask_b32_e64 v22, v22, v212, vcc
.LBB0_774:
	v_add_u32_e32 v24, 0x72, v76
	v_cmp_gt_u32_e32 vcc, s68, v24
	v_mov_b32_e32 v24, 0xf149f2ca
	v_mov_b32_e32 v25, 0xf149f2ca
	s_waitcnt lgkmcnt(15)
	v_add_f32_e32 v212, v26, v190
	v_cndmask_b32_e64 v25, v25, v212, vcc
.LBB0_776:
	v_add_u32_e32 v26, 0x73, v76
	v_cmp_gt_u32_e32 vcc, s68, v26
	s_waitcnt lgkmcnt(15)
	v_add_f32_e32 v212, v27, v191
	v_cndmask_b32_e64 v24, v24, v212, vcc
.LBB0_778:
	v_add_u32_e32 v26, 0x78, v76
	v_cmp_gt_u32_e32 vcc, s68, v26
	v_mov_b32_e32 v26, 0xf149f2ca
	v_mov_b32_e32 v27, 0xf149f2ca
	s_waitcnt lgkmcnt(15)
	v_add_f32_e32 v212, v28, v192
	v_cndmask_b32_e64 v27, v27, v212, vcc
.LBB0_780:
	v_add_u32_e32 v28, 0x79, v76
	v_cmp_gt_u32_e32 vcc, s68, v28
	s_waitcnt lgkmcnt(15)
	v_add_f32_e32 v212, v29, v193
	v_cndmask_b32_e64 v26, v26, v212, vcc
.LBB0_782:
	v_add_u32_e32 v28, 0x7a, v76
	v_cmp_gt_u32_e32 vcc, s68, v28
	v_mov_b32_e32 v28, 0xf149f2ca
	v_mov_b32_e32 v29, 0xf149f2ca
	s_waitcnt lgkmcnt(15)
	v_add_f32_e32 v212, v30, v194
	v_cndmask_b32_e64 v29, v29, v212, vcc
.LBB0_784:
	v_add_u32_e32 v30, 0x7b, v76
	v_cmp_gt_u32_e32 vcc, s68, v30
	s_waitcnt lgkmcnt(15)
	v_add_f32_e32 v212, v31, v195
	v_cndmask_b32_e64 v28, v28, v212, vcc
.LBB0_786:
	v_or_b32_e32 v30, 0x80, v168
	v_sub_u32_e32 v31, v30, v102
	v_add_u32_e32 v30, s71, v30
	s_movk_i32 s0, 0x81
	v_cmp_gt_u32_e32 vcc, s0, v31
	v_cmp_gt_u32_e64 s[0:1], s68, v30
	s_and_b64 s[74:75], vcc, s[0:1]
	v_mov_b32_e32 v30, 0xf149f2ca
	v_mov_b32_e32 v31, 0xf149f2ca
	s_waitcnt lgkmcnt(15)
	v_add_f32_e32 v212, v0, v196
	v_cndmask_b32_e64 v31, v31, v212, s[74:75]
.LBB0_788:
	v_or_b32_e32 v0, 0x81, v168
	v_sub_u32_e32 v76, v0, v102
	v_add_u32_e32 v0, s71, v0
	s_movk_i32 s0, 0x81
	v_cmp_gt_u32_e32 vcc, s0, v76
	v_cmp_gt_u32_e64 s[0:1], s68, v0
	s_and_b64 s[74:75], vcc, s[0:1]
	s_waitcnt lgkmcnt(14)
	v_add_f32_e32 v212, v1, v197
	v_cndmask_b32_e64 v30, v30, v212, s[74:75]
.LBB0_790:
	v_or_b32_e32 v0, 0x82, v168
	v_sub_u32_e32 v1, v0, v102
	v_add_u32_e32 v0, s71, v0
	s_movk_i32 s0, 0x81
	v_cmp_gt_u32_e32 vcc, s0, v1
	v_cmp_gt_u32_e64 s[0:1], s68, v0
	s_and_b64 s[74:75], vcc, s[0:1]
	v_mov_b32_e32 v0, 0xf149f2ca
	v_mov_b32_e32 v1, 0xf149f2ca
	s_waitcnt lgkmcnt(13)
	v_add_f32_e32 v212, v2, v198
	v_cndmask_b32_e64 v1, v1, v212, s[74:75]
.LBB0_792:
	v_or_b32_e32 v2, 0x83, v168
	v_sub_u32_e32 v76, v2, v102
	v_add_u32_e32 v2, s71, v2
	s_movk_i32 s0, 0x81
	v_cmp_gt_u32_e32 vcc, s0, v76
	v_cmp_gt_u32_e64 s[0:1], s68, v2
	s_and_b64 s[74:75], vcc, s[0:1]
	s_waitcnt lgkmcnt(12)
	v_add_f32_e32 v212, v3, v199
	v_cndmask_b32_e64 v0, v0, v212, s[74:75]
; __device__ __forceinline__ void attn_item(const Params& P, int slice, int item, LAS unsigned char* lds) {
;     ...
;   float mx = -3.0e38f;
; #pragma unroll
;   for (int kt = 0; kt < 5; ++kt)
; #pragma unroll
;     for (int i = 0; i < 16; ++i) {
;       const int keyl = 32 * kt + (i & 3) + 8 * (i >> 2) + 4 * h; const int delta = keyl - 64 - qn; const int km = m0 - 64 + 32 * wq + keyl;
;       const bool valid = (delta >= -64) && (delta <= 64) && (km >= 0) && (km < M);
;       int bi = delta + 64; bi = bi < 0 ? 0 : (bi > 128 ? 128 : bi);
;       const float sv = valid ? sc[kt][i] + bl[bi] : -1e30f;
;       sc[kt][i] = sv; mx = fmaxf(mx, sv);
;     }
;   mx = fmaxf(mx, __shfl_xor(mx, 32));
.LBB0_794:
	v_or_b32_e32 v2, 0x88, v168
	v_sub_u32_e32 v3, v2, v102
	v_add_u32_e32 v2, s71, v2
	s_movk_i32 s0, 0x81
	v_cmp_gt_u32_e32 vcc, s0, v3
	v_cmp_gt_u32_e64 s[0:1], s68, v2
	s_and_b64 s[74:75], vcc, s[0:1]
	v_mov_b32_e32 v2, 0xf149f2ca
	v_mov_b32_e32 v3, 0xf149f2ca
	s_waitcnt lgkmcnt(11)
	v_add_f32_e32 v212, v4, v200
	v_cndmask_b32_e64 v3, v3, v212, s[74:75]
.LBB0_796:
	v_or_b32_e32 v4, 0x89, v168
	v_sub_u32_e32 v76, v4, v102
	v_add_u32_e32 v4, s71, v4
	s_movk_i32 s0, 0x81
	v_cmp_gt_u32_e32 vcc, s0, v76
	v_cmp_gt_u32_e64 s[0:1], s68, v4
	s_and_b64 s[74:75], vcc, s[0:1]
	s_waitcnt lgkmcnt(10)
	v_add_f32_e32 v212, v5, v201
	v_cndmask_b32_e64 v2, v2, v212, s[74:75]
.LBB0_798:
	v_or_b32_e32 v4, 0x8a, v168
	v_sub_u32_e32 v5, v4, v102
	v_add_u32_e32 v4, s71, v4
	s_movk_i32 s0, 0x81
	v_cmp_gt_u32_e32 vcc, s0, v5
	v_cmp_gt_u32_e64 s[0:1], s68, v4
	s_and_b64 s[74:75], vcc, s[0:1]
	v_mov_b32_e32 v4, 0xf149f2ca
	v_mov_b32_e32 v5, 0xf149f2ca
	s_waitcnt lgkmcnt(9)
	v_add_f32_e32 v212, v6, v202
	v_cndmask_b32_e64 v5, v5, v212, s[74:75]
.LBB0_800:
	v_or_b32_e32 v6, 0x8b, v168
	v_sub_u32_e32 v76, v6, v102
	v_add_u32_e32 v6, s71, v6
	s_movk_i32 s0, 0x81
	v_cmp_gt_u32_e32 vcc, s0, v76
	v_cmp_gt_u32_e64 s[0:1], s68, v6
	s_and_b64 s[74:75], vcc, s[0:1]
	s_waitcnt lgkmcnt(8)
	v_add_f32_e32 v212, v7, v203
	v_cndmask_b32_e64 v4, v4, v212, s[74:75]
.LBB0_802:
	v_or_b32_e32 v6, 0x90, v168
	v_sub_u32_e32 v7, v6, v102
	v_add_u32_e32 v6, s71, v6
	s_movk_i32 s0, 0x81
	v_cmp_gt_u32_e32 vcc, s0, v7
	v_cmp_gt_u32_e64 s[0:1], s68, v6
	s_and_b64 s[74:75], vcc, s[0:1]
	v_mov_b32_e32 v6, 0xf149f2ca
	v_mov_b32_e32 v7, 0xf149f2ca
	s_waitcnt lgkmcnt(7)
	v_add_f32_e32 v212, v8, v204
	v_cndmask_b32_e64 v7, v7, v212, s[74:75]
.LBB0_804:
	v_or_b32_e32 v8, 0x91, v168
	v_sub_u32_e32 v76, v8, v102
	v_add_u32_e32 v8, s71, v8
	s_movk_i32 s0, 0x81
	v_cmp_gt_u32_e32 vcc, s0, v76
	v_cmp_gt_u32_e64 s[0:1], s68, v8
	s_and_b64 s[74:75], vcc, s[0:1]
	s_waitcnt lgkmcnt(6)
	v_add_f32_e32 v212, v9, v205
	v_cndmask_b32_e64 v6, v6, v212, s[74:75]
.LBB0_806:
	v_or_b32_e32 v8, 0x92, v168
	v_sub_u32_e32 v9, v8, v102
	v_add_u32_e32 v8, s71, v8
	s_movk_i32 s0, 0x81
	v_cmp_gt_u32_e32 vcc, s0, v9
	v_cmp_gt_u32_e64 s[0:1], s68, v8
	s_and_b64 s[74:75], vcc, s[0:1]
	v_mov_b32_e32 v8, 0xf149f2ca
	v_mov_b32_e32 v9, 0xf149f2ca
	s_waitcnt lgkmcnt(5)
	v_add_f32_e32 v212, v10, v206
	v_cndmask_b32_e64 v9, v9, v212, s[74:75]
.LBB0_808:
	v_or_b32_e32 v10, 0x93, v168
	v_sub_u32_e32 v76, v10, v102
	v_add_u32_e32 v10, s71, v10
	s_movk_i32 s0, 0x81
	v_cmp_gt_u32_e32 vcc, s0, v76
	v_cmp_gt_u32_e64 s[0:1], s68, v10
	s_and_b64 s[74:75], vcc, s[0:1]
	s_waitcnt lgkmcnt(4)
	v_add_f32_e32 v212, v11, v207
	v_cndmask_b32_e64 v8, v8, v212, s[74:75]
.LBB0_810:
	v_or_b32_e32 v10, 0x98, v168
	v_sub_u32_e32 v11, v10, v102
	v_add_u32_e32 v10, s71, v10
	s_movk_i32 s0, 0x81
	v_cmp_gt_u32_e32 vcc, s0, v11
	v_cmp_gt_u32_e64 s[0:1], s68, v10
	s_and_b64 s[74:75], vcc, s[0:1]
	v_mov_b32_e32 v10, 0xf149f2ca
	v_mov_b32_e32 v11, 0xf149f2ca
	s_waitcnt lgkmcnt(3)
	v_add_f32_e32 v212, v12, v208
	v_cndmask_b32_e64 v11, v11, v212, s[74:75]
.LBB0_812:
	v_or_b32_e32 v12, 0x99, v168
	v_sub_u32_e32 v76, v12, v102
	v_add_u32_e32 v12, s71, v12
	s_movk_i32 s0, 0x81
	v_cmp_gt_u32_e32 vcc, s0, v76
	v_cmp_gt_u32_e64 s[0:1], s68, v12
	s_and_b64 s[74:75], vcc, s[0:1]
	s_waitcnt lgkmcnt(2)
	v_add_f32_e32 v212, v13, v209
	v_cndmask_b32_e64 v10, v10, v212, s[74:75]
.LBB0_814:
	v_or_b32_e32 v12, 0x9a, v168
	v_sub_u32_e32 v13, v12, v102
	v_add_u32_e32 v12, s71, v12
	s_movk_i32 s0, 0x81
	v_cmp_gt_u32_e32 vcc, s0, v13
	v_cmp_gt_u32_e64 s[0:1], s68, v12
	s_and_b64 s[74:75], vcc, s[0:1]
	v_mov_b32_e32 v12, 0xf149f2ca
	v_mov_b32_e32 v13, 0xf149f2ca
	s_waitcnt lgkmcnt(1)
	v_add_f32_e32 v212, v14, v210
	v_cndmask_b32_e64 v13, v13, v212, s[74:75]
.LBB0_816:
	v_or_b32_e32 v14, 0x9b, v168
	v_sub_u32_e32 v76, v14, v102
	v_add_u32_e32 v14, s71, v14
	s_movk_i32 s0, 0x81
	v_cmp_gt_u32_e32 vcc, s0, v76
	v_cmp_gt_u32_e64 s[0:1], s68, v14
	s_and_b64 s[74:75], vcc, s[0:1]
	s_waitcnt lgkmcnt(0)
	v_add_f32_e32 v212, v15, v211
	v_cndmask_b32_e64 v12, v12, v212, s[74:75]
.LBB0_818:
	s_mov_b32 s0, 0xff61b1e6
	v_max3_f32 v14, v83, s0, v82
	v_max3_f32 v14, v14, v65, v64
	v_max3_f32 v14, v14, v67, v66
	v_max3_f32 v14, v14, v69, v68
	v_max3_f32 v14, v14, v71, v70
	v_max3_f32 v14, v14, v73, v72
	v_max3_f32 v14, v14, v75, v74
	v_max3_f32 v14, v14, v87, v86
	v_max3_f32 v14, v14, v89, v88
	v_max3_f32 v14, v14, v49, v48
	v_max3_f32 v14, v14, v51, v50
	v_max3_f32 v14, v14, v53, v52
	v_max3_f32 v14, v14, v55, v54
	v_max3_f32 v14, v14, v57, v56
	v_max3_f32 v14, v14, v59, v58
	v_max3_f32 v14, v14, v61, v60
	v_max3_f32 v14, v14, v63, v62
	v_max3_f32 v14, v14, v33, v32
	v_max3_f32 v14, v14, v35, v34
	v_max3_f32 v14, v14, v37, v36
	v_max3_f32 v14, v14, v39, v38
	v_max3_f32 v14, v14, v41, v40
	v_max3_f32 v14, v14, v43, v42
	v_max3_f32 v14, v14, v45, v44
	v_max3_f32 v14, v14, v47, v46
	v_max3_f32 v14, v14, v17, v16
	v_max3_f32 v14, v14, v19, v18
	v_max3_f32 v14, v14, v21, v20
	v_max3_f32 v14, v14, v23, v22
	v_max3_f32 v14, v14, v25, v24
	v_max3_f32 v14, v14, v27, v26
	v_max3_f32 v14, v14, v29, v28
	v_max3_f32 v14, v14, v31, v30
	v_max3_f32 v14, v14, v1, v0
	v_max3_f32 v14, v14, v3, v2
	v_max3_f32 v14, v14, v5, v4
	v_max3_f32 v14, v14, v7, v6
	v_max3_f32 v14, v14, v9, v8
	v_max3_f32 v14, v14, v11, v10
	v_max3_f32 v14, v14, v13, v12
	ds_bpermute_b32 v15, v170, v14
	s_waitcnt lgkmcnt(0)
; __device__ __forceinline__ void attn_item(const Params& P, int slice, int item, LAS unsigned char* lds) {
;     ...
;   mx = fmaxf(mx, __shfl_xor(mx, 32));
;   float den = 0.f;
; #pragma unroll
;   for (int kt = 0; kt < 5; ++kt)
; #pragma unroll
;     for (int i = 0; i < 16; ++i) { const float pe = __expf(sc[kt][i] - mx); sc[kt][i] = pe; den += pe; }
;   den += __shfl_xor(den, 32);
;   const float inv = 1.0f / den;
	v_max_f32_e32 v15, v15, v15
	v_max_f32_e32 v14, v14, v15
	v_sub_f32_e32 v15, v83, v14
	v_sub_f32_e32 v76, v82, v14
	v_sub_f32_e32 v65, v65, v14
	v_mul_f32_e32 v15, 0x3fb8aa3b, v15
	v_mul_f32_e32 v77, 0x3fb8aa3b, v76
	v_exp_f32_e32 v76, v15
	v_mul_f32_e32 v15, 0x3fb8aa3b, v65
	v_exp_f32_e32 v78, v15
	v_sub_f32_e32 v15, v64, v14
	v_sub_f32_e32 v64, v67, v14
	v_mul_f32_e32 v64, 0x3fb8aa3b, v64
	v_exp_f32_e32 v84, v64
	v_sub_f32_e32 v64, v66, v14
	v_mul_f32_e32 v64, 0x3fb8aa3b, v64
	v_exp_f32_e32 v85, v64
	v_sub_f32_e32 v64, v69, v14
	v_mul_f32_e32 v64, 0x3fb8aa3b, v64
	v_exp_f32_e32 v90, v64
	v_sub_f32_e32 v64, v68, v14
	v_mul_f32_e32 v64, 0x3fb8aa3b, v64
	v_exp_f32_e32 v91, v64
	v_sub_f32_e32 v64, v71, v14
	v_mul_f32_e32 v64, 0x3fb8aa3b, v64
	v_exp_f32_e32 v66, v64
	v_sub_f32_e32 v64, v70, v14
	v_mul_f32_e32 v64, 0x3fb8aa3b, v64
	v_exp_f32_e32 v67, v64
	v_sub_f32_e32 v64, v73, v14
	v_mul_f32_e32 v64, 0x3fb8aa3b, v64
	v_exp_f32_e32 v68, v64
	v_sub_f32_e32 v64, v72, v14
	v_mul_f32_e32 v64, 0x3fb8aa3b, v64
	v_exp_f32_e32 v77, v77
	v_exp_f32_e32 v69, v64
	v_sub_f32_e32 v64, v75, v14
	v_mul_f32_e32 v15, 0x3fb8aa3b, v15
	v_mul_f32_e32 v64, 0x3fb8aa3b, v64
	v_exp_f32_e32 v79, v15
	v_exp_f32_e32 v70, v64
	v_sub_f32_e32 v64, v74, v14
	v_sub_f32_e32 v48, v48, v14
	v_add_f32_e32 v15, 0, v76
	v_mul_f32_e32 v64, 0x3fb8aa3b, v64
	v_mul_f32_e32 v48, 0x3fb8aa3b, v48
	v_add_f32_e32 v15, v77, v15
	v_exp_f32_e32 v71, v64
	v_sub_f32_e32 v64, v87, v14
	v_exp_f32_e32 v83, v48
	v_sub_f32_e32 v48, v51, v14
	v_add_f32_e32 v15, v78, v15
	v_mul_f32_e32 v64, 0x3fb8aa3b, v64
	v_mul_f32_e32 v48, 0x3fb8aa3b, v48
	v_add_f32_e32 v15, v79, v15
	v_exp_f32_e32 v74, v64
	v_sub_f32_e32 v64, v86, v14
	v_exp_f32_e32 v86, v48
	v_sub_f32_e32 v48, v50, v14
	v_add_f32_e32 v15, v84, v15
	v_mul_f32_e32 v48, 0x3fb8aa3b, v48
	v_add_f32_e32 v15, v85, v15
	v_exp_f32_e32 v87, v48
	v_sub_f32_e32 v48, v53, v14
	v_add_f32_e32 v15, v90, v15
	v_mul_f32_e32 v48, 0x3fb8aa3b, v48
	v_add_f32_e32 v15, v91, v15
	v_exp_f32_e32 v92, v48
	v_sub_f32_e32 v48, v52, v14
	v_add_f32_e32 v15, v66, v15
	v_mul_f32_e32 v64, 0x3fb8aa3b, v64
	v_mul_f32_e32 v48, 0x3fb8aa3b, v48
	v_add_f32_e32 v15, v67, v15
	v_exp_f32_e32 v75, v64
	v_sub_f32_e32 v64, v89, v14
	v_exp_f32_e32 v93, v48
	v_sub_f32_e32 v48, v55, v14
	v_add_f32_e32 v15, v68, v15
	v_mul_f32_e32 v64, 0x3fb8aa3b, v64
	v_mul_f32_e32 v48, 0x3fb8aa3b, v48
	v_add_f32_e32 v15, v69, v15
	v_exp_f32_e32 v72, v64
	v_sub_f32_e32 v64, v88, v14
	v_exp_f32_e32 v88, v48
	v_sub_f32_e32 v48, v54, v14
	v_add_f32_e32 v15, v70, v15
	v_mul_f32_e32 v64, 0x3fb8aa3b, v64
	v_sub_f32_e32 v49, v49, v14
	v_mul_f32_e32 v48, 0x3fb8aa3b, v48
	v_add_f32_e32 v15, v71, v15
	v_exp_f32_e32 v73, v64
	v_mul_f32_e32 v49, 0x3fb8aa3b, v49
	v_exp_f32_e32 v89, v48
	v_sub_f32_e32 v48, v57, v14
	v_add_f32_e32 v15, v74, v15
	v_exp_f32_e32 v82, v49
	v_mul_f32_e32 v48, 0x3fb8aa3b, v48
	v_add_f32_e32 v15, v75, v15
	v_exp_f32_e32 v94, v48
	v_sub_f32_e32 v48, v56, v14
	v_sub_f32_e32 v32, v32, v14
	v_add_f32_e32 v15, v72, v15
	v_mul_f32_e32 v48, 0x3fb8aa3b, v48
	v_mul_f32_e32 v32, 0x3fb8aa3b, v32
	v_add_f32_e32 v15, v73, v15
	v_exp_f32_e32 v95, v48
	v_sub_f32_e32 v48, v59, v14
	v_exp_f32_e32 v105, v32
	v_sub_f32_e32 v32, v35, v14
	v_add_f32_e32 v15, v82, v15
	v_mul_f32_e32 v48, 0x3fb8aa3b, v48
	v_mul_f32_e32 v32, 0x3fb8aa3b, v32
	v_add_f32_e32 v15, v83, v15
	v_exp_f32_e32 v96, v48
	v_sub_f32_e32 v48, v58, v14
	v_exp_f32_e32 v108, v32
	v_sub_f32_e32 v32, v34, v14
	v_add_f32_e32 v15, v86, v15
	v_mul_f32_e32 v48, 0x3fb8aa3b, v48
	v_mul_f32_e32 v32, 0x3fb8aa3b, v32
	v_add_f32_e32 v15, v87, v15
	v_exp_f32_e32 v97, v48
	v_sub_f32_e32 v48, v61, v14
	v_exp_f32_e32 v109, v32
	v_sub_f32_e32 v32, v37, v14
	v_add_f32_e32 v15, v92, v15
	v_mul_f32_e32 v48, 0x3fb8aa3b, v48
	v_mul_f32_e32 v32, 0x3fb8aa3b, v32
	v_add_f32_e32 v15, v93, v15
	v_exp_f32_e32 v102, v48
	v_sub_f32_e32 v48, v60, v14
	v_exp_f32_e32 v112, v32
	v_sub_f32_e32 v32, v36, v14
	v_add_f32_e32 v15, v88, v15
	v_mul_f32_e32 v48, 0x3fb8aa3b, v48
	v_mul_f32_e32 v32, 0x3fb8aa3b, v32
	v_add_f32_e32 v15, v89, v15
	v_exp_f32_e32 v103, v48
	v_sub_f32_e32 v48, v63, v14
	v_exp_f32_e32 v113, v32
	v_sub_f32_e32 v32, v39, v14
	v_add_f32_e32 v15, v94, v15
	v_mul_f32_e32 v48, 0x3fb8aa3b, v48
	v_mul_f32_e32 v32, 0x3fb8aa3b, v32
	v_add_f32_e32 v15, v95, v15
	v_exp_f32_e32 v100, v48
	v_sub_f32_e32 v48, v62, v14
	v_exp_f32_e32 v110, v32
	v_sub_f32_e32 v32, v38, v14
	v_add_f32_e32 v15, v96, v15
	v_mul_f32_e32 v48, 0x3fb8aa3b, v48
	v_sub_f32_e32 v33, v33, v14
	v_mul_f32_e32 v32, 0x3fb8aa3b, v32
	v_add_f32_e32 v15, v97, v15
	v_exp_f32_e32 v101, v48
	v_mul_f32_e32 v33, 0x3fb8aa3b, v33
	v_exp_f32_e32 v111, v32
	v_sub_f32_e32 v32, v41, v14
	v_add_f32_e32 v15, v102, v15
	v_exp_f32_e32 v104, v33
	v_mul_f32_e32 v32, 0x3fb8aa3b, v32
	v_add_f32_e32 v15, v103, v15
	v_exp_f32_e32 v114, v32
	v_sub_f32_e32 v32, v40, v14
	v_sub_f32_e32 v16, v16, v14
	v_add_f32_e32 v15, v100, v15
	v_mul_f32_e32 v32, 0x3fb8aa3b, v32
	v_mul_f32_e32 v16, 0x3fb8aa3b, v16
	v_add_f32_e32 v15, v101, v15
	v_exp_f32_e32 v115, v32
	v_sub_f32_e32 v32, v43, v14
	v_exp_f32_e32 v123, v16
	v_sub_f32_e32 v16, v19, v14
	v_add_f32_e32 v15, v104, v15
	v_mul_f32_e32 v32, 0x3fb8aa3b, v32
	v_mul_f32_e32 v16, 0x3fb8aa3b, v16
	v_add_f32_e32 v15, v105, v15
	v_exp_f32_e32 v116, v32
	v_sub_f32_e32 v32, v42, v14
	v_exp_f32_e32 v124, v16
	v_sub_f32_e32 v16, v18, v14
; __device__ __forceinline__ void attn_item(const Params& P, int slice, int item, LAS unsigned char* lds) {
;     ...
;     for (int i = 0; i < 16; ++i) { const float pe = __expf(sc[kt][i] - mx); sc[kt][i] = pe; den += pe; }
;   den += __shfl_xor(den, 32);
;   const float inv = 1.0f / den;
;   if (h == 0) ((float*)(ws + O_LSE))[((size_t)(gi * 4 + g)) * TS + b * L + r * M + mq] = mx + __logf(den);
	v_add_f32_e32 v15, v108, v15
	v_mul_f32_e32 v32, 0x3fb8aa3b, v32
	v_mul_f32_e32 v16, 0x3fb8aa3b, v16
	v_add_f32_e32 v15, v109, v15
	v_exp_f32_e32 v117, v32
	v_sub_f32_e32 v32, v45, v14
	v_exp_f32_e32 v125, v16
	v_sub_f32_e32 v16, v21, v14
	v_add_f32_e32 v15, v112, v15
	v_mul_f32_e32 v32, 0x3fb8aa3b, v32
	v_mul_f32_e32 v16, 0x3fb8aa3b, v16
	v_add_f32_e32 v15, v113, v15
	v_exp_f32_e32 v120, v32
	v_sub_f32_e32 v32, v44, v14
	v_exp_f32_e32 v128, v16
	v_sub_f32_e32 v16, v20, v14
	v_add_f32_e32 v15, v110, v15
	v_mul_f32_e32 v32, 0x3fb8aa3b, v32
	v_mul_f32_e32 v16, 0x3fb8aa3b, v16
	v_add_f32_e32 v15, v111, v15
	v_exp_f32_e32 v121, v32
	v_sub_f32_e32 v32, v47, v14
	v_exp_f32_e32 v129, v16
	v_sub_f32_e32 v16, v23, v14
	v_add_f32_e32 v15, v114, v15
	v_mul_f32_e32 v32, 0x3fb8aa3b, v32
	v_mul_f32_e32 v16, 0x3fb8aa3b, v16
	v_add_f32_e32 v15, v115, v15
	v_exp_f32_e32 v118, v32
	v_sub_f32_e32 v32, v46, v14
	v_exp_f32_e32 v126, v16
	v_sub_f32_e32 v16, v22, v14
	v_add_f32_e32 v15, v116, v15
	v_mul_f32_e32 v32, 0x3fb8aa3b, v32
	v_sub_f32_e32 v17, v17, v14
	v_mul_f32_e32 v16, 0x3fb8aa3b, v16
	v_add_f32_e32 v15, v117, v15
	v_exp_f32_e32 v119, v32
	v_mul_f32_e32 v17, 0x3fb8aa3b, v17
	v_exp_f32_e32 v127, v16
	v_sub_f32_e32 v16, v25, v14
	v_add_f32_e32 v15, v120, v15
	v_exp_f32_e32 v122, v17
	v_mul_f32_e32 v16, 0x3fb8aa3b, v16
	v_add_f32_e32 v15, v121, v15
	v_exp_f32_e32 v130, v16
	v_sub_f32_e32 v16, v24, v14
	v_add_f32_e32 v15, v118, v15
	v_mul_f32_e32 v16, 0x3fb8aa3b, v16
	v_add_f32_e32 v15, v119, v15
	v_exp_f32_e32 v131, v16
	v_sub_f32_e32 v16, v27, v14
	v_sub_f32_e32 v1, v1, v14
	v_add_f32_e32 v15, v122, v15
	v_mul_f32_e32 v16, 0x3fb8aa3b, v16
	v_mul_f32_e32 v1, 0x3fb8aa3b, v1
	v_add_f32_e32 v15, v123, v15
	v_exp_f32_e32 v132, v16
	v_sub_f32_e32 v16, v26, v14
	v_exp_f32_e32 v138, v1
	v_sub_f32_e32 v1, v3, v14
	v_add_f32_e32 v15, v124, v15
	v_mul_f32_e32 v16, 0x3fb8aa3b, v16
	v_mul_f32_e32 v1, 0x3fb8aa3b, v1
	v_add_f32_e32 v15, v125, v15
	v_exp_f32_e32 v133, v16
	v_sub_f32_e32 v16, v29, v14
	v_exp_f32_e32 v140, v1
	v_sub_f32_e32 v1, v2, v14
	v_add_f32_e32 v15, v128, v15
	v_mul_f32_e32 v16, 0x3fb8aa3b, v16
	v_mul_f32_e32 v1, 0x3fb8aa3b, v1
	v_add_f32_e32 v15, v129, v15
	v_exp_f32_e32 v136, v16
	v_sub_f32_e32 v16, v28, v14
	v_exp_f32_e32 v141, v1
	v_sub_f32_e32 v1, v5, v14
	v_add_f32_e32 v15, v126, v15
	v_mul_f32_e32 v16, 0x3fb8aa3b, v16
	v_mul_f32_e32 v1, 0x3fb8aa3b, v1
	v_add_f32_e32 v15, v127, v15
	v_exp_f32_e32 v137, v16
	v_sub_f32_e32 v16, v31, v14
	v_exp_f32_e32 v144, v1
	v_sub_f32_e32 v1, v4, v14
	v_add_f32_e32 v15, v130, v15
	v_mul_f32_e32 v16, 0x3fb8aa3b, v16
	v_mul_f32_e32 v1, 0x3fb8aa3b, v1
	v_add_f32_e32 v15, v131, v15
	v_exp_f32_e32 v134, v16
	v_sub_f32_e32 v16, v30, v14
	v_exp_f32_e32 v145, v1
	v_sub_f32_e32 v1, v7, v14
	v_add_f32_e32 v15, v132, v15
	v_mul_f32_e32 v16, 0x3fb8aa3b, v16
	v_mul_f32_e32 v1, 0x3fb8aa3b, v1
	v_add_f32_e32 v15, v133, v15
	v_exp_f32_e32 v135, v16
	v_sub_f32_e32 v0, v0, v14
	v_exp_f32_e32 v142, v1
	v_sub_f32_e32 v1, v6, v14
	v_add_f32_e32 v15, v136, v15
	v_mul_f32_e32 v0, 0x3fb8aa3b, v0
	v_mul_f32_e32 v1, 0x3fb8aa3b, v1
	v_add_f32_e32 v15, v137, v15
	v_exp_f32_e32 v139, v0
	v_exp_f32_e32 v143, v1
	v_sub_f32_e32 v1, v9, v14
	v_add_f32_e32 v0, v134, v15
	v_mul_f32_e32 v1, 0x3fb8aa3b, v1
	v_add_f32_e32 v0, v135, v0
	v_exp_f32_e32 v146, v1
	v_sub_f32_e32 v1, v8, v14
	v_add_f32_e32 v0, v138, v0
	v_mul_f32_e32 v1, 0x3fb8aa3b, v1
	v_add_f32_e32 v0, v139, v0
	v_exp_f32_e32 v147, v1
	v_sub_f32_e32 v1, v11, v14
	v_add_f32_e32 v0, v140, v0
	v_mul_f32_e32 v1, 0x3fb8aa3b, v1
	v_add_f32_e32 v0, v141, v0
	v_exp_f32_e32 v148, v1
	v_sub_f32_e32 v1, v10, v14
	v_add_f32_e32 v0, v144, v0
	v_mul_f32_e32 v1, 0x3fb8aa3b, v1
	v_add_f32_e32 v0, v145, v0
	v_exp_f32_e32 v149, v1
	v_sub_f32_e32 v1, v13, v14
	v_add_f32_e32 v0, v142, v0
	v_mul_f32_e32 v1, 0x3fb8aa3b, v1
	v_add_f32_e32 v0, v143, v0
	v_exp_f32_e32 v150, v1
	v_sub_f32_e32 v1, v12, v14
	v_add_f32_e32 v0, v146, v0
	v_mul_f32_e32 v1, 0x3fb8aa3b, v1
	v_add_f32_e32 v0, v147, v0
	v_exp_f32_e32 v151, v1
	v_add_f32_e32 v0, v148, v0
	v_add_f32_e32 v0, v149, v0
	v_add_f32_e32 v0, v150, v0
	v_add_f32_e32 v0, v151, v0
	ds_bpermute_b32 v1, v170, v0
	v_and_b32_e32 v2, 63, v107
	v_cmp_gt_u32_e32 vcc, 32, v2
	s_waitcnt lgkmcnt(0)
	v_add_f32_e32 v65, v0, v1
	s_and_saveexec_b64 s[0:1], vcc
	s_cbranch_execz .LBB0_820
	s_mov_b32 s31, 0x800000
	v_cmp_gt_f32_e32 vcc, s31, v65
	s_mov_b32 s71, 0x3f317217
	v_mov_b32_e32 v1, 0x41b17218
	v_cndmask_b32_e64 v0, 0, 32, vcc
	v_ldexp_f32 v0, v65, v0
	v_log_f32_e32 v0, v0
	s_mov_b32 s74, s84
	s_ashr_i32 s75, s84, 31
	v_cndmask_b32_e32 v1, 0, v1, vcc
	v_mul_f32_e32 v2, 0x3f317217, v0
	v_fma_f32 v2, v0, s71, -v2
	s_mov_b32 s71, 0x7f800000
	v_cmp_lt_f32_e64 vcc, |v0|, s71
	s_mul_i32 s71, s69, s68
	s_lshl_b64 s[68:69], s[74:75], 16
	s_add_u32 s68, s4, s68
	v_fmac_f32_e32 v2, 0x3377d1cf, v0
	s_addc_u32 s69, s5, s69
	s_lshl_b32 s70, s70, 2
	v_fmac_f32_e32 v2, 0x3f317217, v0
	s_add_u32 s68, s68, s70
	v_cndmask_b32_e32 v0, v0, v2, vcc
	s_addc_u32 s69, s69, 0
	s_lshl_b32 s70, s71, 2
	v_sub_f32_e32 v0, v0, v1
	s_add_u32 s68, s68, s70
	v_add_f32_e32 v2, v14, v0
	s_addc_u32 s69, s69, 0
	v_lshlrev_b32_e32 v0, 2, v169
	v_mov_b32_e32 v1, v81
	v_lshl_add_u64 v[0:1], s[68:69], 0, v[0:1]
	v_add_co_u32_e32 v0, vcc, 0x30852000, v0
	s_nop 1
	v_addc_co_u32_e32 v1, vcc, 0, v1, vcc
	flat_store_dword v[0:1], v2
